# 12a/12c: loop-top vmcnt waits no longer cover the stores issued right before the back edge (preheader drains once)
# speedup vs baseline: 1.0107x; 1.0075x over previous
; DI void peer_u_phase(const Params& p) {
;     ...
;   const int g = blockIdx.x & 7, rank = blockIdx.x >> 3, nrank = gridDim.x >> 3;
;   if (rank >= nrank) return;
;   const int q = lane >> 3, s = lane & 7;
;   const bf16_t* H3 = (const bf16_t*)(p.ws + OFF_H3) + 128 * g + 16 * s;
;   const unsigned char* Ub = (const unsigned char*)(p.ws + OFF_UB) + (size_t)g * (16384 * 128) + 16 * s;
;   const int* EID = (const int*)(p.ws + OFF_EID);
;   float* PART = (float*)(p.ws + OFF_PART) + (size_t)g * T_TOK * 128;
;   const int first = rank * 4 + wave, stride = nrank * 4;
;   const int n = (T_TOK - first + stride - 1) / stride;
;   auto tokof = [&](int k) { return first + (k < n ? k : n - 1) * stride; };
;   auto gather = [&](PeerRows& r, const int* e, int tok) {
; #pragma unroll
;     for (int i = 0; i < 16; ++i) r.u[i] = *(const u32x4*)(Ub + (size_t)e[i] * 128);
;     r.xa = *(const uint4*)(H3 + (size_t)tok * 1024);
;     r.xb = *(const uint4*)(H3 + (size_t)tok * 1024 + 8);
;   };
;     ...
;   int ea[16], eb[16];
;   PeerRows ga, gb;
;   peer_load_e(ea, EID, tokof(0), q);
;   peer_load_e(eb, EID, tokof(1), q);
;   gather(ga, ea, tokof(0));
.LBB0_1351:
	s_or_b64 exec, exec, s[4:5]
	s_lshr_b32 s1, s80, 3
	s_lshr_b32 s0, s88, 3
	s_cmp_lt_u32 s1, s0
	v_mov_b32_e32 v38, v192
	s_cselect_b64 s[10:11], -1, 0
	s_cmp_ge_u32 s1, s0
	s_waitcnt lgkmcnt(0)
	s_barrier
	s_cbranch_scc1 .LBB0_1358
	s_lshl_b32 s3, s0, 2
	v_cvt_f32_u32_e32 v0, s3
	v_ashrrev_i32_e32 v1, 6, v38
	s_waitcnt vmcnt(4)
	v_lshl_add_u32 v160, s1, 2, v1
	v_sub_u32_e32 v1, s3, v160
	v_rcp_iflag_f32_e32 v0, v0
	v_add_u32_e32 v1, 0x3fff, v1
	s_sub_i32 s2, 0, s3
	v_sub_u32_e32 v3, 0, v1
	v_mul_f32_e32 v0, 0x4f7ffffe, v0
	v_cvt_u32_f32_e32 v0, v0
	v_ashrrev_i32_e32 v2, 31, v1
	v_max_i32_e32 v1, v1, v3
	v_mul_lo_u32 v3, s2, v0
	v_mul_hi_u32 v3, v0, v3
	v_add_u32_e32 v0, v0, v3
	v_mul_hi_u32 v0, v1, v0
	v_mul_lo_u32 v3, v0, s3
	v_sub_u32_e32 v1, v1, v3
	v_add_u32_e32 v4, 1, v0
	v_cmp_le_u32_e32 vcc, s3, v1
	v_subrev_u32_e32 v3, s3, v1
	s_nop 0
	v_cndmask_b32_e32 v0, v0, v4, vcc
	v_cndmask_b32_e32 v1, v1, v3, vcc
	v_add_u32_e32 v3, 1, v0
	v_cmp_le_u32_e32 vcc, s3, v1
	s_nop 1
	v_cndmask_b32_e32 v0, v0, v3, vcc
	v_xor_b32_e32 v0, v0, v2
	v_sub_u32_e32 v182, v0, v2
	v_cmp_lt_i32_e32 vcc, 0, v182
	s_and_saveexec_b64 s[12:13], vcc
	s_cbranch_execz .LBB0_1357
	s_and_b32 s4, s80, 7
	s_lshl_b32 s2, s4, 8
	s_add_u32 s6, s42, s2
	s_addc_u32 s7, s43, 0
	s_lshl_b32 s2, s4, 21
	v_lshlrev_b32_e32 v0, 4, v38
	s_add_u32 s8, s86, s2
	v_and_b32_e32 v36, 0x70, v0
	v_mov_b32_e32 v37, 0
	s_addc_u32 s9, s87, 0
	v_lshlrev_b32_e32 v0, 3, v38
	v_ashrrev_i32_e32 v161, 31, v160
	v_lshlrev_b32_e32 v12, 1, v36
	v_lshl_add_u64 v[14:15], s[8:9], 0, v[36:37]
	v_and_b32_e32 v36, 0x1c0, v0
	v_lshlrev_b64 v[0:1], 9, v[160:161]
	v_lshl_add_u64 v[0:1], s[86:87], 0, v[0:1]
	v_lshl_add_u64 v[16:17], v[0:1], 0, v[36:37]
	global_load_dwordx4 v[0:3], v[16:17], off offset:48
	global_load_dwordx4 v[4:7], v[16:17], off offset:32
	global_load_dwordx4 v[8:11], v[16:17], off offset:16
	global_load_dwordx4 v[44:47], v[16:17], off
	v_mov_b32_e32 v13, v37
	v_lshlrev_b64 v[16:17], 11, v[160:161]
	v_lshl_add_u64 v[162:163], s[6:7], 0, v[12:13]
	v_lshl_add_u64 v[12:13], v[162:163], 0, v[16:17]
	s_mov_b64 s[8:9], 0x8000000
	global_load_dwordx4 v[76:79], v[12:13], off offset:16
	global_load_dwordx4 v[84:87], v[12:13], off
	v_lshl_add_u64 v[164:165], v[14:15], 0, s[8:9]
	v_add_u32_e32 v183, -1, v182
	v_mov_b32_e32 v39, s3
	v_cmp_ne_u32_e32 vcc, 0, v183
	v_lshl_add_u64 v[166:167], s[86:87], 0, v[36:37]
	s_lshl_b32 s2, s4, 23
	v_cndmask_b32_e32 v39, 0, v39, vcc
	s_add_u32 s14, s86, s2
	s_addc_u32 s15, s87, 0
	s_mov_b32 s18, 3
	s_lshl_b32 s19, s0, 3
	v_mov_b32_e32 v170, v160
	s_waitcnt vmcnt(5)
	v_ashrrev_i32_e32 v13, 31, v3
	v_mov_b32_e32 v12, v3
	s_waitcnt vmcnt(3)
	v_ashrrev_i32_e32 v23, 31, v9
	v_mov_b32_e32 v22, v9
	v_ashrrev_i32_e32 v9, 31, v8
	s_waitcnt vmcnt(2)
	v_ashrrev_i32_e32 v25, 31, v47
	v_mov_b32_e32 v24, v47
	v_ashrrev_i32_e32 v47, 31, v46
	v_ashrrev_i32_e32 v3, 31, v2
	v_ashrrev_i32_e32 v15, 31, v1
	v_mov_b32_e32 v14, v1
	v_ashrrev_i32_e32 v1, 31, v0
	v_ashrrev_i32_e32 v17, 31, v7
	v_mov_b32_e32 v16, v7
	v_ashrrev_i32_e32 v7, 31, v6
	v_ashrrev_i32_e32 v19, 31, v5
	v_mov_b32_e32 v18, v5
	v_ashrrev_i32_e32 v5, 31, v4
	v_ashrrev_i32_e32 v21, 31, v11
	v_mov_b32_e32 v20, v11
	v_ashrrev_i32_e32 v11, 31, v10
	v_lshlrev_b64 v[12:13], 7, v[12:13]
	v_lshlrev_b64 v[8:9], 7, v[8:9]
	v_lshlrev_b64 v[22:23], 7, v[22:23]
	v_lshlrev_b64 v[46:47], 7, v[46:47]
	v_lshlrev_b64 v[24:25], 7, v[24:25]
	v_lshlrev_b64 v[2:3], 7, v[2:3]
	v_lshlrev_b64 v[0:1], 7, v[0:1]
	v_lshlrev_b64 v[14:15], 7, v[14:15]
	v_lshlrev_b64 v[6:7], 7, v[6:7]
	v_lshlrev_b64 v[16:17], 7, v[16:17]
	v_lshlrev_b64 v[4:5], 7, v[4:5]
	v_lshlrev_b64 v[18:19], 7, v[18:19]
	v_lshlrev_b64 v[10:11], 7, v[10:11]
	v_lshlrev_b64 v[20:21], 7, v[20:21]
	v_lshl_add_u64 v[48:49], v[164:165], 0, v[12:13]
	v_lshl_add_u64 v[80:81], v[164:165], 0, v[22:23]
	v_lshl_add_u64 v[82:83], v[164:165], 0, v[8:9]
	v_lshl_add_u64 v[88:89], v[164:165], 0, v[24:25]
	v_lshl_add_u64 v[46:47], v[164:165], 0, v[46:47]
	v_lshl_add_u64 v[50:51], v[164:165], 0, v[2:3]
	v_lshl_add_u64 v[56:57], v[164:165], 0, v[14:15]
	v_lshl_add_u64 v[58:59], v[164:165], 0, v[0:1]
	v_lshl_add_u64 v[64:65], v[164:165], 0, v[16:17]
	v_lshl_add_u64 v[66:67], v[164:165], 0, v[6:7]
	v_lshl_add_u64 v[68:69], v[164:165], 0, v[18:19]
	v_lshl_add_u64 v[70:71], v[164:165], 0, v[4:5]
	v_lshl_add_u64 v[72:73], v[164:165], 0, v[20:21]
	v_lshl_add_u64 v[74:75], v[164:165], 0, v[10:11]
	global_load_dwordx4 v[0:3], v[48:49], off
	global_load_dwordx4 v[4:7], v[50:51], off
	global_load_dwordx4 v[8:11], v[56:57], off
	global_load_dwordx4 v[12:15], v[58:59], off
	global_load_dwordx4 v[16:19], v[64:65], off
	global_load_dwordx4 v[20:23], v[66:67], off
	global_load_dwordx4 v[24:27], v[68:69], off
	global_load_dwordx4 v[28:31], v[70:71], off
	global_load_dwordx4 v[32:35], v[72:73], off
	global_load_dwordx4 v[40:43], v[74:75], off
	global_load_dwordx4 v[52:55], v[80:81], off
	global_load_dwordx4 v[60:63], v[82:83], off
	s_nop 0
	global_load_dwordx4 v[80:83], v[88:89], off
	global_load_dwordx4 v[92:95], v[46:47], off
	v_ashrrev_i32_e32 v47, 31, v45
	v_mov_b32_e32 v46, v45
	v_ashrrev_i32_e32 v45, 31, v44
	v_lshlrev_b64 v[44:45], 7, v[44:45]
	v_lshlrev_b64 v[46:47], 7, v[46:47]
	v_lshl_add_u64 v[46:47], v[164:165], 0, v[46:47]
	v_lshl_add_u64 v[44:45], v[164:165], 0, v[44:45]
	global_load_dwordx4 v[104:107], v[46:47], off
	global_load_dwordx4 v[112:115], v[44:45], off
	v_add_u32_e32 v44, v39, v160
	v_ashrrev_i32_e32 v45, 31, v44
	v_lshlrev_b64 v[44:45], 9, v[44:45]
	v_lshl_add_u64 v[44:45], s[86:87], 0, v[44:45]
	v_lshl_add_u64 v[44:45], v[44:45], 0, v[36:37]
	global_load_dwordx4 v[136:139], v[44:45], off offset:48
	global_load_dwordx4 v[140:143], v[44:45], off offset:32
	global_load_dwordx4 v[144:147], v[44:45], off offset:16
	global_load_dwordx4 v[148:151], v[44:45], off
	v_and_b32_e32 v36, 4, v38
	v_cmp_eq_u32_e32 vcc, 0, v36
	v_mbcnt_lo_u32_b32 v36, -1, 0
	v_mbcnt_hi_u32_b32 v36, -1, v36
	v_and_b32_e32 v45, 64, v36
	v_xor_b32_e32 v44, 4, v36
	v_add_u32_e32 v45, 64, v45
	v_cmp_lt_i32_e64 s[4:5], v44, v45
	v_and_b32_e32 v39, 63, v38
	s_nop 0
	v_cndmask_b32_e64 v44, v36, v44, s[4:5]
	v_lshlrev_b32_e32 v161, 2, v44
	v_and_b32_e32 v44, 2, v38
	v_cmp_eq_u32_e64 s[4:5], 0, v44
	v_xor_b32_e32 v44, 2, v36
	v_cmp_lt_i32_e64 s[6:7], v44, v45
	v_and_b32_e32 v38, 1, v38
	s_nop 0
	v_cndmask_b32_e64 v44, v36, v44, s[6:7]
	v_cmp_eq_u32_e64 s[6:7], 0, v38
	v_xor_b32_e32 v38, 1, v36
	v_cmp_lt_i32_e64 s[8:9], v38, v45
	v_lshlrev_b32_e32 v184, 2, v44
	s_nop 0
	v_cndmask_b32_e64 v36, v36, v38, s[8:9]
	v_lshlrev_b32_e32 v185, 2, v36
	v_lshlrev_b32_e32 v36, 3, v39
	v_lshl_add_u64 v[36:37], s[14:15], 0, v[36:37]
	s_mov_b64 s[8:9], 0x1000000
	v_lshl_add_u64 v[168:169], v[36:37], 0, s[8:9]
	s_mov_b64 s[14:15], 0
	s_waitcnt vmcnt(0)
	s_branch .LBB0_1355

; DI void peer_u_phase(const Params& p) {
;     ...
;   auto gather = [&](PeerRows& r, const int* e, int tok) {
; #pragma unroll
;     for (int i = 0; i < 16; ++i) r.u[i] = *(const u32x4*)(Ub + (size_t)e[i] * 128);
;     r.xa = *(const uint4*)(H3 + (size_t)tok * 1024);
;     r.xb = *(const uint4*)(H3 + (size_t)tok * 1024 + 8);
;   };
;   auto compute = [&](const PeerRows& r, int tok) {
;     f32x2 x2[8];
;     {
;       float x[16];
;       unpack8(r.xa, x);
;       unpack8(r.xb, x + 8);
; #pragma unroll
;       for (int k = 0; k < 8; ++k) { x2[k][0] = x[2 * k]; x2[k][1] = x[2 * k + 1]; }
;     }
;     float pr[16];
; #pragma unroll
;     for (int i = 0; i < 16; ++i) {
;       f32x2 aA = {0.f, 0.f}, aB = {0.f, 0.f};
; #pragma unroll
;       for (int j = 0; j < 4; ++j) {
;         const f32x2 lo = __builtin_amdgcn_cvt_pk_f32_fp8((int)r.u[i][j], false);
;         const f32x2 hi = __builtin_amdgcn_cvt_pk_f32_fp8((int)r.u[i][j], true);
;         aA = __builtin_elementwise_fma(lo, x2[2 * j], aA);
;         aB = __builtin_elementwise_fma(hi, x2[2 * j + 1], aB);
;       }
;       aA += aB;
;       pr[i] = aA[0] + aA[1];
;     ...
;     peer_load_e(ea, EID, tokof(k + 2), q);
;     gather(gb, eb, tokof(k + 1));
;     __builtin_amdgcn_sched_barrier(0);
;     compute(ga, tokof(k));
.LBB0_1355:
	s_add_i32 s20, s18, -1
	v_min_i32_e32 v36, s20, v183
	v_mad_u64_u32 v[174:175], s[8:9], v36, s3, v[160:161]
	v_ashrrev_i32_e32 v175, 31, v174
	v_lshlrev_b64 v[36:37], 9, v[174:175]
	s_add_i32 s8, s18, -2
	v_lshl_add_u64 v[176:177], v[166:167], 0, v[36:37]
	v_min_i32_e32 v36, s8, v183
	v_mad_u64_u32 v[172:173], s[16:17], v36, s3, v[160:161]
	s_waitcnt vmcnt(1)
	v_ashrrev_i32_e32 v37, 31, v148
	v_mov_b32_e32 v36, v148
	v_ashrrev_i32_e32 v39, 31, v149
	v_mov_b32_e32 v38, v149
	v_lshlrev_b64 v[36:37], 7, v[36:37]
	v_lshlrev_b64 v[38:39], 7, v[38:39]
	v_lshl_add_u64 v[36:37], v[164:165], 0, v[36:37]
	v_lshl_add_u64 v[38:39], v[164:165], 0, v[38:39]
	global_load_dwordx4 v[132:135], v[36:37], off
	global_load_dwordx4 v[128:131], v[38:39], off
	v_ashrrev_i32_e32 v37, 31, v150
	v_mov_b32_e32 v36, v150
	v_ashrrev_i32_e32 v39, 31, v151
	v_mov_b32_e32 v38, v151
	v_lshlrev_b64 v[36:37], 7, v[36:37]
	v_lshlrev_b64 v[38:39], 7, v[38:39]
	v_lshl_add_u64 v[36:37], v[164:165], 0, v[36:37]
	v_lshl_add_u64 v[38:39], v[164:165], 0, v[38:39]
	global_load_dwordx4 v[124:127], v[36:37], off
	global_load_dwordx4 v[120:123], v[38:39], off
	v_ashrrev_i32_e32 v37, 31, v144
	v_mov_b32_e32 v36, v144
	v_ashrrev_i32_e32 v39, 31, v145
	v_mov_b32_e32 v38, v145
	v_lshlrev_b64 v[36:37], 7, v[36:37]
	v_lshlrev_b64 v[38:39], 7, v[38:39]
	v_lshl_add_u64 v[36:37], v[164:165], 0, v[36:37]
	v_lshl_add_u64 v[38:39], v[164:165], 0, v[38:39]
	global_load_dwordx4 v[116:119], v[36:37], off
	global_load_dwordx4 v[108:111], v[38:39], off
	v_ashrrev_i32_e32 v37, 31, v146
	v_mov_b32_e32 v36, v146
	v_ashrrev_i32_e32 v39, 31, v147
	v_mov_b32_e32 v38, v147
	v_lshlrev_b64 v[36:37], 7, v[36:37]
	v_lshlrev_b64 v[38:39], 7, v[38:39]
	v_lshl_add_u64 v[36:37], v[164:165], 0, v[36:37]
	v_lshl_add_u64 v[38:39], v[164:165], 0, v[38:39]
	global_load_dwordx4 v[100:103], v[36:37], off
	global_load_dwordx4 v[96:99], v[38:39], off
	v_ashrrev_i32_e32 v37, 31, v140
	v_mov_b32_e32 v36, v140
	v_ashrrev_i32_e32 v39, 31, v141
	v_mov_b32_e32 v38, v141
	v_lshlrev_b64 v[36:37], 7, v[36:37]
	v_lshlrev_b64 v[38:39], 7, v[38:39]
	v_lshl_add_u64 v[36:37], v[164:165], 0, v[36:37]
	v_lshl_add_u64 v[38:39], v[164:165], 0, v[38:39]
	global_load_dwordx4 v[88:91], v[36:37], off
	global_load_dwordx4 v[72:75], v[38:39], off
	v_ashrrev_i32_e32 v37, 31, v142
	v_mov_b32_e32 v36, v142
	v_ashrrev_i32_e32 v39, 31, v143
	v_mov_b32_e32 v38, v143
	v_lshlrev_b64 v[36:37], 7, v[36:37]
	v_lshlrev_b64 v[38:39], 7, v[38:39]
	v_lshl_add_u64 v[36:37], v[164:165], 0, v[36:37]
	v_lshl_add_u64 v[38:39], v[164:165], 0, v[38:39]
	global_load_dwordx4 v[68:71], v[36:37], off
	global_load_dwordx4 v[64:67], v[38:39], off
	v_ashrrev_i32_e32 v37, 31, v136
	v_mov_b32_e32 v36, v136
	v_ashrrev_i32_e32 v39, 31, v137
	v_mov_b32_e32 v38, v137
	v_lshlrev_b64 v[36:37], 7, v[36:37]
	v_lshlrev_b64 v[38:39], 7, v[38:39]
	v_lshl_add_u64 v[36:37], v[164:165], 0, v[36:37]
	v_lshl_add_u64 v[38:39], v[164:165], 0, v[38:39]
	global_load_dwordx4 v[56:59], v[36:37], off
	global_load_dwordx4 v[48:51], v[38:39], off
	v_ashrrev_i32_e32 v37, 31, v138
	v_mov_b32_e32 v36, v138
	v_ashrrev_i32_e32 v39, 31, v139
	v_mov_b32_e32 v38, v139
	v_ashrrev_i32_e32 v173, 31, v172
	v_cvt_pk_f32_fp8_e32 v[144:145], v112
	v_cvt_pk_f32_fp8_sdwa v[146:147], v112 src0_sel:WORD_1
	v_lshlrev_b64 v[36:37], 7, v[36:37]
	v_lshlrev_b64 v[38:39], 7, v[38:39]
	v_lshlrev_b64 v[136:137], 11, v[172:173]
	v_cvt_pk_f32_fp8_e32 v[148:149], v113
	v_cvt_pk_f32_fp8_sdwa v[112:113], v113 src0_sel:WORD_1
	v_lshl_add_u64 v[36:37], v[164:165], 0, v[36:37]
	v_lshl_add_u64 v[38:39], v[164:165], 0, v[38:39]
	v_lshl_add_u64 v[136:137], v[162:163], 0, v[136:137]
	global_load_dwordx4 v[44:47], v[36:37], off
	s_nop 0
	global_load_dwordx4 v[36:39], v[38:39], off
	s_nop 0
	global_load_dwordx4 v[152:155], v[136:137], off offset:16
	global_load_dwordx4 v[156:159], v[136:137], off
	v_lshlrev_b32_e32 v136, 16, v84
	v_and_b32_e32 v137, 0xffff0000, v84
	v_lshlrev_b32_e32 v138, 16, v85
	v_and_b32_e32 v139, 0xffff0000, v85
	v_lshlrev_b32_e32 v140, 16, v86
	v_and_b32_e32 v141, 0xffff0000, v86
	v_lshlrev_b32_e32 v142, 16, v87
	v_and_b32_e32 v143, 0xffff0000, v87
	v_pk_fma_f32 v[144:145], v[144:145], v[136:137], 0 op_sel_hi:[1,1,0]
	v_pk_fma_f32 v[146:147], v[146:147], v[138:139], 0 op_sel_hi:[1,1,0]
	v_pk_fma_f32 v[144:145], v[148:149], v[140:141], v[144:145]
	v_pk_fma_f32 v[112:113], v[112:113], v[142:143], v[146:147]
	v_cvt_pk_f32_fp8_e32 v[146:147], v114
	v_cvt_pk_f32_fp8_sdwa v[148:149], v114 src0_sel:WORD_1
	v_cvt_pk_f32_fp8_e32 v[150:151], v115
	v_cvt_pk_f32_fp8_sdwa v[114:115], v115 src0_sel:WORD_1
	v_lshlrev_b32_e32 v84, 16, v76
	v_and_b32_e32 v85, 0xffff0000, v76
	v_lshlrev_b32_e32 v76, 16, v77
	v_and_b32_e32 v77, 0xffff0000, v77
	v_lshlrev_b32_e32 v86, 16, v78
	v_and_b32_e32 v87, 0xffff0000, v78
	v_lshlrev_b32_e32 v78, 16, v79
	v_and_b32_e32 v79, 0xffff0000, v79
	v_pk_fma_f32 v[144:145], v[146:147], v[84:85], v[144:145]
	v_pk_fma_f32 v[112:113], v[148:149], v[76:77], v[112:113]
	v_pk_fma_f32 v[144:145], v[150:151], v[86:87], v[144:145]
	v_pk_fma_f32 v[112:113], v[114:115], v[78:79], v[112:113]
	v_cvt_pk_f32_fp8_e32 v[114:115], v104
	v_pk_add_f32 v[112:113], v[144:145], v[112:113]
	v_cvt_pk_f32_fp8_sdwa v[144:145], v104 src0_sel:WORD_1
	v_cvt_pk_f32_fp8_e32 v[146:147], v105
	v_cvt_pk_f32_fp8_sdwa v[104:105], v105 src0_sel:WORD_1
	v_pk_fma_f32 v[114:115], v[114:115], v[136:137], 0 op_sel_hi:[1,1,0]
	v_pk_fma_f32 v[144:145], v[144:145], v[138:139], 0 op_sel_hi:[1,1,0]
	v_pk_fma_f32 v[114:115], v[146:147], v[140:141], v[114:115]
	v_pk_fma_f32 v[104:105], v[104:105], v[142:143], v[144:145]
	v_cvt_pk_f32_fp8_e32 v[144:145], v106
; DI void peer_u_phase(const Params& p) {
;     ...
;     float pr[16];
; #pragma unroll
;     for (int i = 0; i < 16; ++i) {
;       f32x2 aA = {0.f, 0.f}, aB = {0.f, 0.f};
; #pragma unroll
;       for (int j = 0; j < 4; ++j) {
;         const f32x2 lo = __builtin_amdgcn_cvt_pk_f32_fp8((int)r.u[i][j], false);
;         const f32x2 hi = __builtin_amdgcn_cvt_pk_f32_fp8((int)r.u[i][j], true);
;         aA = __builtin_elementwise_fma(lo, x2[2 * j], aA);
;         aB = __builtin_elementwise_fma(hi, x2[2 * j + 1], aB);
;       }
;       aA += aB;
;       pr[i] = aA[0] + aA[1];
;     }
	v_cvt_pk_f32_fp8_sdwa v[146:147], v106 src0_sel:WORD_1
	v_cvt_pk_f32_fp8_e32 v[148:149], v107
	v_cvt_pk_f32_fp8_sdwa v[106:107], v107 src0_sel:WORD_1
	v_pk_fma_f32 v[114:115], v[144:145], v[84:85], v[114:115]
	v_pk_fma_f32 v[104:105], v[146:147], v[76:77], v[104:105]
	v_pk_fma_f32 v[114:115], v[148:149], v[86:87], v[114:115]
	v_pk_fma_f32 v[104:105], v[106:107], v[78:79], v[104:105]
	v_cvt_pk_f32_fp8_e32 v[106:107], v92
	v_pk_add_f32 v[104:105], v[114:115], v[104:105]
	v_cvt_pk_f32_fp8_sdwa v[114:115], v92 src0_sel:WORD_1
	v_cvt_pk_f32_fp8_e32 v[144:145], v93
	v_cvt_pk_f32_fp8_sdwa v[92:93], v93 src0_sel:WORD_1
	v_pk_fma_f32 v[106:107], v[106:107], v[136:137], 0 op_sel_hi:[1,1,0]
	v_pk_fma_f32 v[114:115], v[114:115], v[138:139], 0 op_sel_hi:[1,1,0]
	v_pk_fma_f32 v[106:107], v[144:145], v[140:141], v[106:107]
	v_pk_fma_f32 v[92:93], v[92:93], v[142:143], v[114:115]
	v_cvt_pk_f32_fp8_e32 v[114:115], v94
	v_cvt_pk_f32_fp8_sdwa v[144:145], v94 src0_sel:WORD_1
	v_cvt_pk_f32_fp8_e32 v[146:147], v95
	v_cvt_pk_f32_fp8_sdwa v[94:95], v95 src0_sel:WORD_1
	v_pk_fma_f32 v[106:107], v[114:115], v[84:85], v[106:107]
	v_pk_fma_f32 v[92:93], v[144:145], v[76:77], v[92:93]
	v_pk_fma_f32 v[106:107], v[146:147], v[86:87], v[106:107]
	v_pk_fma_f32 v[92:93], v[94:95], v[78:79], v[92:93]
	v_cvt_pk_f32_fp8_e32 v[94:95], v80
	v_pk_add_f32 v[92:93], v[106:107], v[92:93]
	v_cvt_pk_f32_fp8_sdwa v[106:107], v80 src0_sel:WORD_1
	v_cvt_pk_f32_fp8_e32 v[114:115], v81
	v_cvt_pk_f32_fp8_sdwa v[80:81], v81 src0_sel:WORD_1
	v_pk_fma_f32 v[94:95], v[94:95], v[136:137], 0 op_sel_hi:[1,1,0]
	v_pk_fma_f32 v[106:107], v[106:107], v[138:139], 0 op_sel_hi:[1,1,0]
	v_pk_fma_f32 v[94:95], v[114:115], v[140:141], v[94:95]
	v_pk_fma_f32 v[80:81], v[80:81], v[142:143], v[106:107]
	v_cvt_pk_f32_fp8_e32 v[106:107], v82
	v_cvt_pk_f32_fp8_sdwa v[114:115], v82 src0_sel:WORD_1
	v_cvt_pk_f32_fp8_e32 v[144:145], v83
	v_cvt_pk_f32_fp8_sdwa v[82:83], v83 src0_sel:WORD_1
	v_pk_fma_f32 v[94:95], v[106:107], v[84:85], v[94:95]
	v_pk_fma_f32 v[80:81], v[114:115], v[76:77], v[80:81]
	v_pk_fma_f32 v[94:95], v[144:145], v[86:87], v[94:95]
	v_pk_fma_f32 v[80:81], v[82:83], v[78:79], v[80:81]
	v_cvt_pk_f32_fp8_e32 v[82:83], v60
	v_pk_add_f32 v[80:81], v[94:95], v[80:81]
	v_cvt_pk_f32_fp8_sdwa v[94:95], v60 src0_sel:WORD_1
	v_cvt_pk_f32_fp8_e32 v[106:107], v61
	v_cvt_pk_f32_fp8_sdwa v[60:61], v61 src0_sel:WORD_1
	v_pk_fma_f32 v[82:83], v[82:83], v[136:137], 0 op_sel_hi:[1,1,0]
	v_pk_fma_f32 v[94:95], v[94:95], v[138:139], 0 op_sel_hi:[1,1,0]
	v_pk_fma_f32 v[82:83], v[106:107], v[140:141], v[82:83]
	v_pk_fma_f32 v[60:61], v[60:61], v[142:143], v[94:95]
	v_cvt_pk_f32_fp8_e32 v[94:95], v62
	v_cvt_pk_f32_fp8_sdwa v[106:107], v62 src0_sel:WORD_1
	v_cvt_pk_f32_fp8_e32 v[114:115], v63
	v_cvt_pk_f32_fp8_sdwa v[62:63], v63 src0_sel:WORD_1
	v_pk_fma_f32 v[82:83], v[94:95], v[84:85], v[82:83]
	v_pk_fma_f32 v[60:61], v[106:107], v[76:77], v[60:61]
	v_pk_fma_f32 v[82:83], v[114:115], v[86:87], v[82:83]
	v_pk_fma_f32 v[60:61], v[62:63], v[78:79], v[60:61]
	v_cvt_pk_f32_fp8_e32 v[62:63], v52
	v_pk_add_f32 v[60:61], v[82:83], v[60:61]
	v_cvt_pk_f32_fp8_sdwa v[82:83], v52 src0_sel:WORD_1
	v_cvt_pk_f32_fp8_e32 v[94:95], v53
	v_cvt_pk_f32_fp8_sdwa v[52:53], v53 src0_sel:WORD_1
	v_pk_fma_f32 v[62:63], v[62:63], v[136:137], 0 op_sel_hi:[1,1,0]
	v_pk_fma_f32 v[82:83], v[82:83], v[138:139], 0 op_sel_hi:[1,1,0]
	v_pk_fma_f32 v[62:63], v[94:95], v[140:141], v[62:63]
	v_pk_fma_f32 v[52:53], v[52:53], v[142:143], v[82:83]
	v_cvt_pk_f32_fp8_e32 v[82:83], v54
	v_cvt_pk_f32_fp8_sdwa v[94:95], v54 src0_sel:WORD_1
	v_cvt_pk_f32_fp8_e32 v[106:107], v55
	v_cvt_pk_f32_fp8_sdwa v[54:55], v55 src0_sel:WORD_1
	v_pk_fma_f32 v[62:63], v[82:83], v[84:85], v[62:63]
	v_pk_fma_f32 v[52:53], v[94:95], v[76:77], v[52:53]
	v_pk_fma_f32 v[62:63], v[106:107], v[86:87], v[62:63]
	v_pk_fma_f32 v[52:53], v[54:55], v[78:79], v[52:53]
	v_cvt_pk_f32_fp8_e32 v[54:55], v40
	v_pk_add_f32 v[52:53], v[62:63], v[52:53]
	v_cvt_pk_f32_fp8_sdwa v[62:63], v40 src0_sel:WORD_1
	v_cvt_pk_f32_fp8_e32 v[82:83], v41
	v_cvt_pk_f32_fp8_sdwa v[40:41], v41 src0_sel:WORD_1
	v_pk_fma_f32 v[54:55], v[54:55], v[136:137], 0 op_sel_hi:[1,1,0]
	v_pk_fma_f32 v[62:63], v[62:63], v[138:139], 0 op_sel_hi:[1,1,0]
	v_pk_fma_f32 v[54:55], v[82:83], v[140:141], v[54:55]
	v_pk_fma_f32 v[40:41], v[40:41], v[142:143], v[62:63]
	v_cvt_pk_f32_fp8_e32 v[62:63], v42
	v_cvt_pk_f32_fp8_sdwa v[82:83], v42 src0_sel:WORD_1
	v_cvt_pk_f32_fp8_e32 v[94:95], v43
	v_cvt_pk_f32_fp8_sdwa v[42:43], v43 src0_sel:WORD_1
	v_pk_fma_f32 v[54:55], v[62:63], v[84:85], v[54:55]
	v_pk_fma_f32 v[40:41], v[82:83], v[76:77], v[40:41]
	v_pk_fma_f32 v[54:55], v[94:95], v[86:87], v[54:55]
	v_pk_fma_f32 v[40:41], v[42:43], v[78:79], v[40:41]
	v_cvt_pk_f32_fp8_e32 v[42:43], v32
	v_pk_add_f32 v[40:41], v[54:55], v[40:41]
	v_cvt_pk_f32_fp8_sdwa v[54:55], v32 src0_sel:WORD_1
	v_cvt_pk_f32_fp8_e32 v[62:63], v33
	v_cvt_pk_f32_fp8_sdwa v[32:33], v33 src0_sel:WORD_1
	v_pk_fma_f32 v[42:43], v[42:43], v[136:137], 0 op_sel_hi:[1,1,0]
	v_pk_fma_f32 v[54:55], v[54:55], v[138:139], 0 op_sel_hi:[1,1,0]
	v_pk_fma_f32 v[42:43], v[62:63], v[140:141], v[42:43]
	v_pk_fma_f32 v[32:33], v[32:33], v[142:143], v[54:55]
	v_cvt_pk_f32_fp8_e32 v[54:55], v34
	v_cvt_pk_f32_fp8_sdwa v[62:63], v34 src0_sel:WORD_1
	v_cvt_pk_f32_fp8_e32 v[82:83], v35
	v_cvt_pk_f32_fp8_sdwa v[34:35], v35 src0_sel:WORD_1
	v_pk_fma_f32 v[42:43], v[54:55], v[84:85], v[42:43]
	v_pk_fma_f32 v[32:33], v[62:63], v[76:77], v[32:33]
	v_pk_fma_f32 v[42:43], v[82:83], v[86:87], v[42:43]
	v_pk_fma_f32 v[32:33], v[34:35], v[78:79], v[32:33]
	v_cvt_pk_f32_fp8_e32 v[34:35], v28
; DI void peer_u_phase(const Params& p) {
;     ...
;     float pr[16];
; #pragma unroll
;     for (int i = 0; i < 16; ++i) {
;       f32x2 aA = {0.f, 0.f}, aB = {0.f, 0.f};
; #pragma unroll
;       for (int j = 0; j < 4; ++j) {
;         const f32x2 lo = __builtin_amdgcn_cvt_pk_f32_fp8((int)r.u[i][j], false);
;         const f32x2 hi = __builtin_amdgcn_cvt_pk_f32_fp8((int)r.u[i][j], true);
;         aA = __builtin_elementwise_fma(lo, x2[2 * j], aA);
;         aB = __builtin_elementwise_fma(hi, x2[2 * j + 1], aB);
;       }
;       aA += aB;
;       pr[i] = aA[0] + aA[1];
;     }
	v_pk_add_f32 v[32:33], v[42:43], v[32:33]
	v_cvt_pk_f32_fp8_sdwa v[42:43], v28 src0_sel:WORD_1
	v_cvt_pk_f32_fp8_e32 v[54:55], v29
	v_cvt_pk_f32_fp8_sdwa v[28:29], v29 src0_sel:WORD_1
	v_pk_fma_f32 v[34:35], v[34:35], v[136:137], 0 op_sel_hi:[1,1,0]
	v_pk_fma_f32 v[42:43], v[42:43], v[138:139], 0 op_sel_hi:[1,1,0]
	v_pk_fma_f32 v[34:35], v[54:55], v[140:141], v[34:35]
	v_pk_fma_f32 v[28:29], v[28:29], v[142:143], v[42:43]
	v_cvt_pk_f32_fp8_e32 v[42:43], v30
	v_cvt_pk_f32_fp8_sdwa v[54:55], v30 src0_sel:WORD_1
	v_cvt_pk_f32_fp8_e32 v[62:63], v31
	v_cvt_pk_f32_fp8_sdwa v[30:31], v31 src0_sel:WORD_1
	v_pk_fma_f32 v[34:35], v[42:43], v[84:85], v[34:35]
	v_pk_fma_f32 v[28:29], v[54:55], v[76:77], v[28:29]
	v_pk_fma_f32 v[34:35], v[62:63], v[86:87], v[34:35]
	v_pk_fma_f32 v[28:29], v[30:31], v[78:79], v[28:29]
	v_cvt_pk_f32_fp8_e32 v[30:31], v24
	v_pk_add_f32 v[28:29], v[34:35], v[28:29]
	v_cvt_pk_f32_fp8_sdwa v[34:35], v24 src0_sel:WORD_1
	v_cvt_pk_f32_fp8_e32 v[42:43], v25
	v_cvt_pk_f32_fp8_sdwa v[24:25], v25 src0_sel:WORD_1
	v_pk_fma_f32 v[30:31], v[30:31], v[136:137], 0 op_sel_hi:[1,1,0]
	v_pk_fma_f32 v[34:35], v[34:35], v[138:139], 0 op_sel_hi:[1,1,0]
	v_pk_fma_f32 v[30:31], v[42:43], v[140:141], v[30:31]
	v_pk_fma_f32 v[24:25], v[24:25], v[142:143], v[34:35]
	v_cvt_pk_f32_fp8_e32 v[34:35], v26
	v_cvt_pk_f32_fp8_sdwa v[42:43], v26 src0_sel:WORD_1
	v_cvt_pk_f32_fp8_e32 v[54:55], v27
	v_cvt_pk_f32_fp8_sdwa v[26:27], v27 src0_sel:WORD_1
	v_pk_fma_f32 v[30:31], v[34:35], v[84:85], v[30:31]
	v_pk_fma_f32 v[24:25], v[42:43], v[76:77], v[24:25]
	v_pk_fma_f32 v[30:31], v[54:55], v[86:87], v[30:31]
	v_pk_fma_f32 v[24:25], v[26:27], v[78:79], v[24:25]
	v_cvt_pk_f32_fp8_e32 v[26:27], v20
	v_pk_add_f32 v[24:25], v[30:31], v[24:25]
	v_cvt_pk_f32_fp8_sdwa v[30:31], v20 src0_sel:WORD_1
	v_cvt_pk_f32_fp8_e32 v[34:35], v21
	v_cvt_pk_f32_fp8_sdwa v[20:21], v21 src0_sel:WORD_1
	v_pk_fma_f32 v[26:27], v[26:27], v[136:137], 0 op_sel_hi:[1,1,0]
	v_pk_fma_f32 v[30:31], v[30:31], v[138:139], 0 op_sel_hi:[1,1,0]
	v_pk_fma_f32 v[26:27], v[34:35], v[140:141], v[26:27]
	v_pk_fma_f32 v[20:21], v[20:21], v[142:143], v[30:31]
	v_cvt_pk_f32_fp8_e32 v[30:31], v22
	v_cvt_pk_f32_fp8_sdwa v[34:35], v22 src0_sel:WORD_1
	v_cvt_pk_f32_fp8_e32 v[42:43], v23
	v_cvt_pk_f32_fp8_sdwa v[22:23], v23 src0_sel:WORD_1
	v_pk_fma_f32 v[26:27], v[30:31], v[84:85], v[26:27]
	v_pk_fma_f32 v[20:21], v[34:35], v[76:77], v[20:21]
	v_pk_fma_f32 v[26:27], v[42:43], v[86:87], v[26:27]
	v_pk_fma_f32 v[20:21], v[22:23], v[78:79], v[20:21]
	v_cvt_pk_f32_fp8_e32 v[22:23], v16
	v_pk_add_f32 v[20:21], v[26:27], v[20:21]
	v_cvt_pk_f32_fp8_sdwa v[26:27], v16 src0_sel:WORD_1
	v_cvt_pk_f32_fp8_e32 v[30:31], v17
	v_cvt_pk_f32_fp8_sdwa v[16:17], v17 src0_sel:WORD_1
	v_pk_fma_f32 v[22:23], v[22:23], v[136:137], 0 op_sel_hi:[1,1,0]
	v_pk_fma_f32 v[26:27], v[26:27], v[138:139], 0 op_sel_hi:[1,1,0]
	v_pk_fma_f32 v[22:23], v[30:31], v[140:141], v[22:23]
	v_pk_fma_f32 v[16:17], v[16:17], v[142:143], v[26:27]
	v_cvt_pk_f32_fp8_e32 v[26:27], v18
	v_cvt_pk_f32_fp8_sdwa v[30:31], v18 src0_sel:WORD_1
	v_cvt_pk_f32_fp8_e32 v[34:35], v19
	v_cvt_pk_f32_fp8_sdwa v[18:19], v19 src0_sel:WORD_1
	v_pk_fma_f32 v[22:23], v[26:27], v[84:85], v[22:23]
	v_pk_fma_f32 v[16:17], v[30:31], v[76:77], v[16:17]
	v_pk_fma_f32 v[22:23], v[34:35], v[86:87], v[22:23]
	v_pk_fma_f32 v[16:17], v[18:19], v[78:79], v[16:17]
	v_cvt_pk_f32_fp8_e32 v[18:19], v12
	v_pk_add_f32 v[16:17], v[22:23], v[16:17]
	v_cvt_pk_f32_fp8_sdwa v[22:23], v12 src0_sel:WORD_1
	v_cvt_pk_f32_fp8_e32 v[26:27], v13
	v_cvt_pk_f32_fp8_sdwa v[12:13], v13 src0_sel:WORD_1
	v_pk_fma_f32 v[18:19], v[18:19], v[136:137], 0 op_sel_hi:[1,1,0]
	v_pk_fma_f32 v[22:23], v[22:23], v[138:139], 0 op_sel_hi:[1,1,0]
	v_pk_fma_f32 v[18:19], v[26:27], v[140:141], v[18:19]
	v_pk_fma_f32 v[12:13], v[12:13], v[142:143], v[22:23]
	v_cvt_pk_f32_fp8_e32 v[22:23], v14
	v_cvt_pk_f32_fp8_sdwa v[26:27], v14 src0_sel:WORD_1
	v_cvt_pk_f32_fp8_e32 v[30:31], v15
	v_cvt_pk_f32_fp8_sdwa v[14:15], v15 src0_sel:WORD_1
	v_pk_fma_f32 v[18:19], v[22:23], v[84:85], v[18:19]
	v_pk_fma_f32 v[12:13], v[26:27], v[76:77], v[12:13]
	v_pk_fma_f32 v[18:19], v[30:31], v[86:87], v[18:19]
	v_pk_fma_f32 v[12:13], v[14:15], v[78:79], v[12:13]
	v_cvt_pk_f32_fp8_e32 v[14:15], v8
	v_pk_add_f32 v[12:13], v[18:19], v[12:13]
	v_cvt_pk_f32_fp8_sdwa v[18:19], v8 src0_sel:WORD_1
	v_cvt_pk_f32_fp8_e32 v[22:23], v9
	v_cvt_pk_f32_fp8_sdwa v[8:9], v9 src0_sel:WORD_1
	v_pk_fma_f32 v[14:15], v[14:15], v[136:137], 0 op_sel_hi:[1,1,0]
	v_pk_fma_f32 v[18:19], v[18:19], v[138:139], 0 op_sel_hi:[1,1,0]
	v_pk_fma_f32 v[14:15], v[22:23], v[140:141], v[14:15]
	v_pk_fma_f32 v[8:9], v[8:9], v[142:143], v[18:19]
	v_cvt_pk_f32_fp8_e32 v[18:19], v10
	v_cvt_pk_f32_fp8_sdwa v[22:23], v10 src0_sel:WORD_1
	v_cvt_pk_f32_fp8_e32 v[26:27], v11
	v_cvt_pk_f32_fp8_sdwa v[10:11], v11 src0_sel:WORD_1
	v_pk_fma_f32 v[14:15], v[18:19], v[84:85], v[14:15]
	v_pk_fma_f32 v[8:9], v[22:23], v[76:77], v[8:9]
	v_pk_fma_f32 v[14:15], v[26:27], v[86:87], v[14:15]
	v_pk_fma_f32 v[8:9], v[10:11], v[78:79], v[8:9]
	v_cvt_pk_f32_fp8_e32 v[10:11], v4
	v_pk_add_f32 v[8:9], v[14:15], v[8:9]
	v_cvt_pk_f32_fp8_sdwa v[14:15], v4 src0_sel:WORD_1
	v_cvt_pk_f32_fp8_e32 v[18:19], v5
	v_cvt_pk_f32_fp8_sdwa v[4:5], v5 src0_sel:WORD_1
	v_pk_fma_f32 v[10:11], v[10:11], v[136:137], 0 op_sel_hi:[1,1,0]
	v_pk_fma_f32 v[14:15], v[14:15], v[138:139], 0 op_sel_hi:[1,1,0]
	v_pk_fma_f32 v[10:11], v[18:19], v[140:141], v[10:11]
	v_pk_fma_f32 v[4:5], v[4:5], v[142:143], v[14:15]
	v_cvt_pk_f32_fp8_e32 v[14:15], v6
	v_cvt_pk_f32_fp8_sdwa v[18:19], v6 src0_sel:WORD_1
	v_cvt_pk_f32_fp8_e32 v[22:23], v7
; DI void peer_load_e(int* e, const int* EID, int tok, int q) {
;   const int4* ep = (const int4*)(EID + (size_t)tok * 128 + 16 * q);
; #pragma unroll
;   for (int j = 0; j < 4; ++j) { const int4 v = ep[j]; e[4 * j] = v.x; e[4 * j + 1] = v.y; e[4 * j + 2] = v.z; e[4 * j + 3] = v.w; }
; }
; DI void peer_u_phase(const Params& p) {
;     ...
;     float pr[16];
; #pragma unroll
;     for (int i = 0; i < 16; ++i) {
;       f32x2 aA = {0.f, 0.f}, aB = {0.f, 0.f};
; #pragma unroll
;       for (int j = 0; j < 4; ++j) {
;         const f32x2 lo = __builtin_amdgcn_cvt_pk_f32_fp8((int)r.u[i][j], false);
;         const f32x2 hi = __builtin_amdgcn_cvt_pk_f32_fp8((int)r.u[i][j], true);
;         aA = __builtin_elementwise_fma(lo, x2[2 * j], aA);
;         aB = __builtin_elementwise_fma(hi, x2[2 * j + 1], aB);
;       }
;       aA += aB;
;       pr[i] = aA[0] + aA[1];
;     }
;     float r8[8], r4[4], r2[2];
; #pragma unroll
;     for (int k = 0; k < 8; ++k) {
;       const float keep = (lane & 4) ? pr[k + 8] : pr[k], send = (lane & 4) ? pr[k] : pr[k + 8];
;       r8[k] = keep + __shfl_xor(send, 4);
;     }
; #pragma unroll
;     for (int k = 0; k < 4; ++k) {
;       const float keep = (lane & 2) ? r8[k + 4] : r8[k], send = (lane & 2) ? r8[k] : r8[k + 4];
;       r4[k] = keep + __shfl_xor(send, 2);
;     }
; #pragma unroll
;     for (int k = 0; k < 2; ++k) {
;       const float keep = (lane & 1) ? r4[k + 2] : r4[k], send = (lane & 1) ? r4[k] : r4[k + 2];
;       r2[k] = keep + __shfl_xor(send, 1);
;     }
;     *(float2*)(PART + (size_t)tok * 128 + 2 * lane) = make_float2(r2[0], r2[1]);
	v_cvt_pk_f32_fp8_sdwa v[6:7], v7 src0_sel:WORD_1
	v_pk_fma_f32 v[10:11], v[14:15], v[84:85], v[10:11]
	v_pk_fma_f32 v[4:5], v[18:19], v[76:77], v[4:5]
	v_pk_fma_f32 v[10:11], v[22:23], v[86:87], v[10:11]
	v_pk_fma_f32 v[4:5], v[6:7], v[78:79], v[4:5]
	v_cvt_pk_f32_fp8_sdwa v[6:7], v0 src0_sel:WORD_1
	v_pk_add_f32 v[10:11], v[10:11], v[4:5]
	v_cvt_pk_f32_fp8_e32 v[4:5], v0
	v_cvt_pk_f32_fp8_e32 v[14:15], v1
	v_cvt_pk_f32_fp8_sdwa v[0:1], v1 src0_sel:WORD_1
	v_pk_fma_f32 v[6:7], v[6:7], v[138:139], 0 op_sel_hi:[1,1,0]
	v_pk_fma_f32 v[4:5], v[4:5], v[136:137], 0 op_sel_hi:[1,1,0]
	v_cvt_pk_f32_fp8_e32 v[18:19], v3
	v_pk_fma_f32 v[4:5], v[14:15], v[140:141], v[4:5]
	v_pk_fma_f32 v[0:1], v[0:1], v[142:143], v[6:7]
	v_cvt_pk_f32_fp8_e32 v[6:7], v2
	v_cvt_pk_f32_fp8_sdwa v[14:15], v2 src0_sel:WORD_1
	v_cvt_pk_f32_fp8_sdwa v[2:3], v3 src0_sel:WORD_1
	v_mov_b32_e32 v30, v40
	v_pk_fma_f32 v[4:5], v[6:7], v[84:85], v[4:5]
	v_pk_fma_f32 v[0:1], v[14:15], v[76:77], v[0:1]
	v_pk_fma_f32 v[4:5], v[18:19], v[86:87], v[4:5]
	v_pk_fma_f32 v[0:1], v[2:3], v[78:79], v[0:1]
	v_mov_b32_e32 v31, v32
	v_mov_b32_e32 v32, v41
	v_pk_add_f32 v[14:15], v[4:5], v[0:1]
	v_mov_b32_e32 v0, v112
	v_mov_b32_e32 v1, v104
	v_mov_b32_e32 v104, v113
	v_pk_add_f32 v[30:31], v[30:31], v[32:33]
	v_mov_b32_e32 v32, v28
	v_mov_b32_e32 v33, v24
	v_mov_b32_e32 v24, v29
	v_mov_b32_e32 v28, v20
	v_mov_b32_e32 v29, v16
	v_mov_b32_e32 v16, v21
	v_mov_b32_e32 v20, v12
	v_mov_b32_e32 v21, v8
	v_mov_b32_e32 v8, v13
	v_pk_add_f32 v[18:19], v[0:1], v[104:105]
	v_pk_add_f32 v[24:25], v[32:33], v[24:25]
	v_pk_add_f32 v[12:13], v[20:21], v[8:9]
	v_mov_b32_e32 v8, v10
	v_mov_b32_e32 v9, v14
	v_mov_b32_e32 v14, v11
	v_mov_b32_e32 v0, v92
	v_mov_b32_e32 v1, v80
	v_mov_b32_e32 v80, v93
	v_pk_add_f32 v[14:15], v[8:9], v[14:15]
	v_cndmask_b32_e32 v8, v18, v24, vcc
	v_pk_add_f32 v[22:23], v[0:1], v[80:81]
	v_pk_add_f32 v[16:17], v[28:29], v[16:17]
	ds_bpermute_b32 v20, v161, v8
	v_cndmask_b32_e32 v8, v19, v25, vcc
	ds_bpermute_b32 v21, v161, v8
	v_cndmask_b32_e32 v8, v22, v16, vcc
	v_mov_b32_e32 v0, v60
	v_mov_b32_e32 v1, v52
	v_mov_b32_e32 v52, v61
	v_cndmask_b32_e32 v28, v24, v18, vcc
	ds_bpermute_b32 v18, v161, v8
	v_cndmask_b32_e32 v8, v23, v17, vcc
	v_pk_add_f32 v[26:27], v[0:1], v[52:53]
	global_load_dwordx4 v[0:3], v[176:177], off offset:16
	global_load_dwordx4 v[4:7], v[176:177], off
	v_cndmask_b32_e32 v29, v25, v19, vcc
	ds_bpermute_b32 v19, v161, v8
	global_load_dwordx4 v[76:79], v[176:177], off offset:48
	global_load_dwordx4 v[8:11], v[176:177], off offset:32
	v_cndmask_b32_e32 v17, v17, v23, vcc
	v_cndmask_b32_e32 v16, v16, v22, vcc
	v_cndmask_b32_e32 v23, v13, v27, vcc
	v_cndmask_b32_e32 v13, v27, v13, vcc
	s_waitcnt lgkmcnt(0)
	v_pk_add_f32 v[16:17], v[16:17], v[18:19]
	v_cndmask_b32_e32 v18, v26, v12, vcc
	ds_bpermute_b32 v19, v161, v13
	v_cndmask_b32_e32 v13, v30, v14, vcc
	ds_bpermute_b32 v18, v161, v18
	ds_bpermute_b32 v24, v161, v13
	v_cndmask_b32_e32 v13, v31, v15, vcc
	ds_bpermute_b32 v25, v161, v13
	v_cndmask_b32_e32 v22, v12, v26, vcc
	v_pk_add_f32 v[20:21], v[28:29], v[20:21]
	s_waitcnt lgkmcnt(2)
	v_pk_add_f32 v[12:13], v[22:23], v[18:19]
	v_cndmask_b32_e32 v15, v15, v31, vcc
	v_cndmask_b32_e32 v14, v14, v30, vcc
	s_waitcnt lgkmcnt(0)
	v_pk_add_f32 v[14:15], v[14:15], v[24:25]
	v_cndmask_b32_e64 v23, v13, v21, s[4:5]
	v_cndmask_b32_e64 v13, v21, v13, s[4:5]
	ds_bpermute_b32 v19, v184, v13
	v_cndmask_b32_e64 v13, v16, v14, s[4:5]
	v_cndmask_b32_e64 v18, v20, v12, s[4:5]
	ds_bpermute_b32 v24, v184, v13
	v_cndmask_b32_e64 v13, v17, v15, s[4:5]
	ds_bpermute_b32 v18, v184, v18
	ds_bpermute_b32 v25, v184, v13
	v_cndmask_b32_e64 v22, v12, v20, s[4:5]
	v_cndmask_b32_e64 v15, v15, v17, s[4:5]
	v_cndmask_b32_e64 v14, v14, v16, s[4:5]
	s_waitcnt lgkmcnt(1)
	v_pk_add_f32 v[12:13], v[22:23], v[18:19]
	s_waitcnt lgkmcnt(0)
	v_pk_add_f32 v[14:15], v[14:15], v[24:25]
	v_ashrrev_i32_e32 v171, 31, v170
	v_cndmask_b32_e64 v16, v12, v14, s[6:7]
	v_cndmask_b32_e64 v17, v13, v15, s[6:7]
	ds_bpermute_b32 v16, v185, v16
	ds_bpermute_b32 v17, v185, v17
	v_cndmask_b32_e64 v13, v15, v13, s[6:7]
	v_cndmask_b32_e64 v12, v14, v12, s[6:7]
	v_min_i32_e32 v14, s18, v183
	v_mad_u64_u32 v[14:15], s[16:17], v14, s3, v[160:161]
	s_waitcnt lgkmcnt(0)
	v_pk_add_f32 v[12:13], v[12:13], v[16:17]
	v_ashrrev_i32_e32 v15, 31, v14
	v_lshlrev_b64 v[18:19], 9, v[170:171]
	v_lshlrev_b64 v[14:15], 9, v[14:15]
	v_lshl_add_u64 v[18:19], v[168:169], 0, v[18:19]
	v_lshl_add_u64 v[14:15], v[166:167], 0, v[14:15]
	s_waitcnt vmcnt(3)
	v_ashrrev_i32_e32 v25, 31, v1
	s_waitcnt vmcnt(2)
	v_ashrrev_i32_e32 v21, 31, v5
	v_mov_b32_e32 v20, v5
	v_ashrrev_i32_e32 v23, 31, v7
	v_mov_b32_e32 v22, v7
	v_mov_b32_e32 v24, v1
	v_ashrrev_i32_e32 v27, 31, v3
	v_mov_b32_e32 v26, v3
	s_waitcnt vmcnt(0)
; DI void peer_u_phase(const Params& p) {
;     ...
;   auto gather = [&](PeerRows& r, const int* e, int tok) {
; #pragma unroll
;     for (int i = 0; i < 16; ++i) r.u[i] = *(const u32x4*)(Ub + (size_t)e[i] * 128);
;     r.xa = *(const uint4*)(H3 + (size_t)tok * 1024);
;     r.xb = *(const uint4*)(H3 + (size_t)tok * 1024 + 8);
;   };
;   auto compute = [&](const PeerRows& r, int tok) {
;     f32x2 x2[8];
;     {
;       float x[16];
;       unpack8(r.xa, x);
;       unpack8(r.xb, x + 8);
; #pragma unroll
;       for (int k = 0; k < 8; ++k) { x2[k][0] = x[2 * k]; x2[k][1] = x[2 * k + 1]; }
;     }
;     float pr[16];
; #pragma unroll
;     for (int i = 0; i < 16; ++i) {
;       f32x2 aA = {0.f, 0.f}, aB = {0.f, 0.f};
; #pragma unroll
;       for (int j = 0; j < 4; ++j) {
;         const f32x2 lo = __builtin_amdgcn_cvt_pk_f32_fp8((int)r.u[i][j], false);
;         const f32x2 hi = __builtin_amdgcn_cvt_pk_f32_fp8((int)r.u[i][j], true);
;         aA = __builtin_elementwise_fma(lo, x2[2 * j], aA);
;         aB = __builtin_elementwise_fma(hi, x2[2 * j + 1], aB);
;       }
;       aA += aB;
;       pr[i] = aA[0] + aA[1];
;     ...
;     *(float2*)(PART + (size_t)tok * 128 + 2 * lane) = make_float2(r2[0], r2[1]);
;   };
;   int ea[16], eb[16];
;   PeerRows ga, gb;
;   peer_load_e(ea, EID, tokof(0), q);
;   peer_load_e(eb, EID, tokof(1), q);
;   gather(ga, ea, tokof(0));
;   for (int k = 0; k < n; k += 2) {
;     peer_load_e(ea, EID, tokof(k + 2), q);
;     gather(gb, eb, tokof(k + 1));
;     __builtin_amdgcn_sched_barrier(0);
;     compute(ga, tokof(k));
;     __builtin_amdgcn_sched_barrier(0);
;     peer_load_e(eb, EID, tokof(k + 3), q);
;     gather(ga, ea, tokof(k + 2));
;     __builtin_amdgcn_sched_barrier(0);
;     if (k + 1 < n) compute(gb, tokof(k + 1));
	v_ashrrev_i32_e32 v29, 31, v9
	v_mov_b32_e32 v28, v9
	v_ashrrev_i32_e32 v17, 31, v4
	v_mov_b32_e32 v16, v4
	v_lshlrev_b64 v[4:5], 7, v[20:21]
	v_ashrrev_i32_e32 v21, 31, v6
	v_mov_b32_e32 v20, v6
	v_lshlrev_b64 v[6:7], 7, v[22:23]
	v_ashrrev_i32_e32 v23, 31, v0
	v_mov_b32_e32 v22, v0
	v_lshlrev_b64 v[0:1], 7, v[24:25]
	v_ashrrev_i32_e32 v25, 31, v2
	v_mov_b32_e32 v24, v2
	v_lshlrev_b64 v[2:3], 7, v[26:27]
	v_ashrrev_i32_e32 v27, 31, v8
	v_mov_b32_e32 v26, v8
	v_lshlrev_b64 v[8:9], 7, v[28:29]
	v_ashrrev_i32_e32 v29, 31, v10
	v_mov_b32_e32 v28, v10
	v_ashrrev_i32_e32 v31, 31, v11
	v_mov_b32_e32 v30, v11
	v_lshlrev_b64 v[28:29], 7, v[28:29]
	v_lshlrev_b64 v[10:11], 7, v[30:31]
	v_lshl_add_u64 v[84:85], v[164:165], 0, v[28:29]
	v_ashrrev_i32_e32 v29, 31, v76
	v_mov_b32_e32 v28, v76
	v_ashrrev_i32_e32 v31, 31, v77
	v_mov_b32_e32 v30, v77
	v_lshlrev_b64 v[16:17], 7, v[16:17]
	v_lshlrev_b64 v[20:21], 7, v[20:21]
	v_lshlrev_b64 v[22:23], 7, v[22:23]
	v_lshlrev_b64 v[24:25], 7, v[24:25]
	v_lshlrev_b64 v[26:27], 7, v[26:27]
	v_lshlrev_b64 v[30:31], 7, v[30:31]
	v_lshlrev_b64 v[28:29], 7, v[28:29]
	v_lshl_add_u64 v[16:17], v[164:165], 0, v[16:17]
	v_lshl_add_u64 v[4:5], v[164:165], 0, v[4:5]
	v_lshl_add_u64 v[20:21], v[164:165], 0, v[20:21]
	v_lshl_add_u64 v[6:7], v[164:165], 0, v[6:7]
	v_lshl_add_u64 v[22:23], v[164:165], 0, v[22:23]
	v_lshl_add_u64 v[0:1], v[164:165], 0, v[0:1]
	v_lshl_add_u64 v[24:25], v[164:165], 0, v[24:25]
	v_lshl_add_u64 v[2:3], v[164:165], 0, v[2:3]
	v_lshl_add_u64 v[26:27], v[164:165], 0, v[26:27]
	v_lshl_add_u64 v[8:9], v[164:165], 0, v[8:9]
	v_lshl_add_u64 v[10:11], v[164:165], 0, v[10:11]
	v_lshl_add_u64 v[76:77], v[164:165], 0, v[28:29]
	v_lshl_add_u64 v[86:87], v[164:165], 0, v[30:31]
	global_store_dwordx2 v[18:19], v[12:13], off
	global_load_dwordx4 v[136:139], v[14:15], off offset:48
	global_load_dwordx4 v[140:143], v[14:15], off offset:32
	global_load_dwordx4 v[144:147], v[14:15], off offset:16
	global_load_dwordx4 v[148:151], v[14:15], off
	global_load_dwordx4 v[112:115], v[16:17], off
	global_load_dwordx4 v[104:107], v[4:5], off
	global_load_dwordx4 v[92:95], v[20:21], off
	global_load_dwordx4 v[80:83], v[6:7], off
	global_load_dwordx4 v[60:63], v[22:23], off
	global_load_dwordx4 v[52:55], v[0:1], off
	global_load_dwordx4 v[40:43], v[24:25], off
	global_load_dwordx4 v[32:35], v[2:3], off
	global_load_dwordx4 v[28:31], v[26:27], off
	s_nop 0
	global_load_dwordx4 v[24:27], v[8:9], off
	global_load_dwordx4 v[20:23], v[84:85], off
	global_load_dwordx4 v[16:19], v[10:11], off
	global_load_dwordx4 v[12:15], v[76:77], off
	s_nop 0
	global_load_dwordx4 v[8:11], v[86:87], off
	v_ashrrev_i32_e32 v1, 31, v78
	v_mov_b32_e32 v0, v78
	v_ashrrev_i32_e32 v3, 31, v79
	v_mov_b32_e32 v2, v79
	v_lshlrev_b64 v[2:3], 7, v[2:3]
	v_lshlrev_b64 v[0:1], 7, v[0:1]
	v_lshlrev_b64 v[76:77], 11, v[174:175]
	v_lshl_add_u64 v[0:1], v[164:165], 0, v[0:1]
	v_lshl_add_u64 v[2:3], v[164:165], 0, v[2:3]
	v_lshl_add_u64 v[84:85], v[162:163], 0, v[76:77]
	global_load_dwordx4 v[4:7], v[0:1], off
	s_nop 0
	global_load_dwordx4 v[0:3], v[2:3], off
	s_nop 0
	global_load_dwordx4 v[76:79], v[84:85], off offset:16
	s_nop 0
	global_load_dwordx4 v[84:87], v[84:85], off
	v_cmp_lt_i32_e64 s[8:9], s8, v182
	s_and_saveexec_b64 s[16:17], s[8:9]
	s_cbranch_execz .LBB0_1354
	v_cvt_pk_f32_fp8_e32 v[186:187], v132
	v_cvt_pk_f32_fp8_sdwa v[188:189], v132 src0_sel:WORD_1
	v_cvt_pk_f32_fp8_e32 v[190:191], v133
	v_cvt_pk_f32_fp8_sdwa v[132:133], v133 src0_sel:WORD_1
	v_lshlrev_b32_e32 v174, 16, v156
	v_and_b32_e32 v175, 0xffff0000, v156
	v_lshlrev_b32_e32 v176, 16, v157
	v_and_b32_e32 v177, 0xffff0000, v157
	v_lshlrev_b32_e32 v178, 16, v158
	v_and_b32_e32 v179, 0xffff0000, v158
	v_lshlrev_b32_e32 v180, 16, v159
	v_and_b32_e32 v181, 0xffff0000, v159
	v_pk_fma_f32 v[186:187], v[186:187], v[174:175], 0 op_sel_hi:[1,1,0]
	v_pk_fma_f32 v[188:189], v[188:189], v[176:177], 0 op_sel_hi:[1,1,0]
	v_pk_fma_f32 v[186:187], v[190:191], v[178:179], v[186:187]
	v_pk_fma_f32 v[132:133], v[132:133], v[180:181], v[188:189]
	v_cvt_pk_f32_fp8_e32 v[188:189], v134
	v_cvt_pk_f32_fp8_sdwa v[190:191], v134 src0_sel:WORD_1
	v_cvt_pk_f32_fp8_e32 v[194:195], v135
	v_cvt_pk_f32_fp8_sdwa v[134:135], v135 src0_sel:WORD_1
	v_lshlrev_b32_e32 v156, 16, v152
	v_and_b32_e32 v157, 0xffff0000, v152
	v_lshlrev_b32_e32 v152, 16, v153
	v_and_b32_e32 v153, 0xffff0000, v153
	v_lshlrev_b32_e32 v158, 16, v154
	v_and_b32_e32 v159, 0xffff0000, v154
	v_lshlrev_b32_e32 v154, 16, v155
	v_and_b32_e32 v155, 0xffff0000, v155
	v_pk_fma_f32 v[186:187], v[188:189], v[156:157], v[186:187]
	v_pk_fma_f32 v[132:133], v[190:191], v[152:153], v[132:133]
	v_pk_fma_f32 v[186:187], v[194:195], v[158:159], v[186:187]
	v_pk_fma_f32 v[132:133], v[134:135], v[154:155], v[132:133]
	v_cvt_pk_f32_fp8_e32 v[134:135], v128
	v_pk_add_f32 v[132:133], v[186:187], v[132:133]
	v_cvt_pk_f32_fp8_sdwa v[186:187], v128 src0_sel:WORD_1
	v_cvt_pk_f32_fp8_e32 v[188:189], v129
	v_cvt_pk_f32_fp8_sdwa v[128:129], v129 src0_sel:WORD_1
	v_pk_fma_f32 v[134:135], v[134:135], v[174:175], 0 op_sel_hi:[1,1,0]
	v_pk_fma_f32 v[186:187], v[186:187], v[176:177], 0 op_sel_hi:[1,1,0]
	v_pk_fma_f32 v[134:135], v[188:189], v[178:179], v[134:135]
	v_pk_fma_f32 v[128:129], v[128:129], v[180:181], v[186:187]
	v_cvt_pk_f32_fp8_e32 v[186:187], v130
	v_cvt_pk_f32_fp8_sdwa v[188:189], v130 src0_sel:WORD_1
	v_cvt_pk_f32_fp8_e32 v[190:191], v131
	v_cvt_pk_f32_fp8_sdwa v[130:131], v131 src0_sel:WORD_1
	v_pk_fma_f32 v[134:135], v[186:187], v[156:157], v[134:135]
	v_pk_fma_f32 v[128:129], v[188:189], v[152:153], v[128:129]
	v_pk_fma_f32 v[134:135], v[190:191], v[158:159], v[134:135]
; DI void peer_u_phase(const Params& p) {
;     ...
;     for (int i = 0; i < 16; ++i) {
;       f32x2 aA = {0.f, 0.f}, aB = {0.f, 0.f};
; #pragma unroll
;       for (int j = 0; j < 4; ++j) {
;         const f32x2 lo = __builtin_amdgcn_cvt_pk_f32_fp8((int)r.u[i][j], false);
;         const f32x2 hi = __builtin_amdgcn_cvt_pk_f32_fp8((int)r.u[i][j], true);
;         aA = __builtin_elementwise_fma(lo, x2[2 * j], aA);
;         aB = __builtin_elementwise_fma(hi, x2[2 * j + 1], aB);
;       }
;       aA += aB;
;       pr[i] = aA[0] + aA[1];
;     }
	v_pk_fma_f32 v[128:129], v[130:131], v[154:155], v[128:129]
	v_cvt_pk_f32_fp8_e32 v[130:131], v124
	v_pk_add_f32 v[128:129], v[134:135], v[128:129]
	v_cvt_pk_f32_fp8_sdwa v[134:135], v124 src0_sel:WORD_1
	v_cvt_pk_f32_fp8_e32 v[186:187], v125
	v_cvt_pk_f32_fp8_sdwa v[124:125], v125 src0_sel:WORD_1
	v_pk_fma_f32 v[130:131], v[130:131], v[174:175], 0 op_sel_hi:[1,1,0]
	v_pk_fma_f32 v[134:135], v[134:135], v[176:177], 0 op_sel_hi:[1,1,0]
	v_pk_fma_f32 v[130:131], v[186:187], v[178:179], v[130:131]
	v_pk_fma_f32 v[124:125], v[124:125], v[180:181], v[134:135]
	v_cvt_pk_f32_fp8_e32 v[134:135], v126
	v_cvt_pk_f32_fp8_sdwa v[186:187], v126 src0_sel:WORD_1
	v_cvt_pk_f32_fp8_e32 v[188:189], v127
	v_cvt_pk_f32_fp8_sdwa v[126:127], v127 src0_sel:WORD_1
	v_pk_fma_f32 v[130:131], v[134:135], v[156:157], v[130:131]
	v_pk_fma_f32 v[124:125], v[186:187], v[152:153], v[124:125]
	v_pk_fma_f32 v[130:131], v[188:189], v[158:159], v[130:131]
	v_pk_fma_f32 v[124:125], v[126:127], v[154:155], v[124:125]
	v_cvt_pk_f32_fp8_e32 v[126:127], v120
	v_pk_add_f32 v[124:125], v[130:131], v[124:125]
	v_cvt_pk_f32_fp8_sdwa v[130:131], v120 src0_sel:WORD_1
	v_cvt_pk_f32_fp8_e32 v[134:135], v121
	v_cvt_pk_f32_fp8_sdwa v[120:121], v121 src0_sel:WORD_1
	v_pk_fma_f32 v[126:127], v[126:127], v[174:175], 0 op_sel_hi:[1,1,0]
	v_pk_fma_f32 v[130:131], v[130:131], v[176:177], 0 op_sel_hi:[1,1,0]
	v_pk_fma_f32 v[126:127], v[134:135], v[178:179], v[126:127]
	v_pk_fma_f32 v[120:121], v[120:121], v[180:181], v[130:131]
	v_cvt_pk_f32_fp8_e32 v[130:131], v122
	v_cvt_pk_f32_fp8_sdwa v[134:135], v122 src0_sel:WORD_1
	v_cvt_pk_f32_fp8_e32 v[186:187], v123
	v_cvt_pk_f32_fp8_sdwa v[122:123], v123 src0_sel:WORD_1
	v_pk_fma_f32 v[126:127], v[130:131], v[156:157], v[126:127]
	v_pk_fma_f32 v[120:121], v[134:135], v[152:153], v[120:121]
	v_pk_fma_f32 v[126:127], v[186:187], v[158:159], v[126:127]
	v_pk_fma_f32 v[120:121], v[122:123], v[154:155], v[120:121]
	v_cvt_pk_f32_fp8_e32 v[122:123], v116
	v_pk_add_f32 v[120:121], v[126:127], v[120:121]
	v_cvt_pk_f32_fp8_sdwa v[126:127], v116 src0_sel:WORD_1
	v_cvt_pk_f32_fp8_e32 v[130:131], v117
	v_cvt_pk_f32_fp8_sdwa v[116:117], v117 src0_sel:WORD_1
	v_pk_fma_f32 v[122:123], v[122:123], v[174:175], 0 op_sel_hi:[1,1,0]
	v_pk_fma_f32 v[126:127], v[126:127], v[176:177], 0 op_sel_hi:[1,1,0]
	v_pk_fma_f32 v[122:123], v[130:131], v[178:179], v[122:123]
	v_pk_fma_f32 v[116:117], v[116:117], v[180:181], v[126:127]
	v_cvt_pk_f32_fp8_e32 v[126:127], v118
	v_cvt_pk_f32_fp8_sdwa v[130:131], v118 src0_sel:WORD_1
	v_cvt_pk_f32_fp8_e32 v[134:135], v119
	v_cvt_pk_f32_fp8_sdwa v[118:119], v119 src0_sel:WORD_1
	v_pk_fma_f32 v[122:123], v[126:127], v[156:157], v[122:123]
	v_pk_fma_f32 v[116:117], v[130:131], v[152:153], v[116:117]
	v_pk_fma_f32 v[122:123], v[134:135], v[158:159], v[122:123]
	v_pk_fma_f32 v[116:117], v[118:119], v[154:155], v[116:117]
	v_cvt_pk_f32_fp8_e32 v[118:119], v108
	v_pk_add_f32 v[116:117], v[122:123], v[116:117]
	v_cvt_pk_f32_fp8_sdwa v[122:123], v108 src0_sel:WORD_1
	v_cvt_pk_f32_fp8_e32 v[126:127], v109
	v_cvt_pk_f32_fp8_sdwa v[108:109], v109 src0_sel:WORD_1
	v_pk_fma_f32 v[118:119], v[118:119], v[174:175], 0 op_sel_hi:[1,1,0]
	v_pk_fma_f32 v[122:123], v[122:123], v[176:177], 0 op_sel_hi:[1,1,0]
	v_pk_fma_f32 v[118:119], v[126:127], v[178:179], v[118:119]
	v_pk_fma_f32 v[108:109], v[108:109], v[180:181], v[122:123]
	v_cvt_pk_f32_fp8_e32 v[122:123], v110
	v_cvt_pk_f32_fp8_sdwa v[126:127], v110 src0_sel:WORD_1
	v_cvt_pk_f32_fp8_e32 v[130:131], v111
	v_cvt_pk_f32_fp8_sdwa v[110:111], v111 src0_sel:WORD_1
	v_pk_fma_f32 v[118:119], v[122:123], v[156:157], v[118:119]
	v_pk_fma_f32 v[108:109], v[126:127], v[152:153], v[108:109]
	v_pk_fma_f32 v[118:119], v[130:131], v[158:159], v[118:119]
	v_pk_fma_f32 v[108:109], v[110:111], v[154:155], v[108:109]
	v_cvt_pk_f32_fp8_e32 v[110:111], v100
	v_pk_add_f32 v[108:109], v[118:119], v[108:109]
	v_cvt_pk_f32_fp8_sdwa v[118:119], v100 src0_sel:WORD_1
	v_cvt_pk_f32_fp8_e32 v[122:123], v101
	v_cvt_pk_f32_fp8_sdwa v[100:101], v101 src0_sel:WORD_1
	v_pk_fma_f32 v[110:111], v[110:111], v[174:175], 0 op_sel_hi:[1,1,0]
	v_pk_fma_f32 v[118:119], v[118:119], v[176:177], 0 op_sel_hi:[1,1,0]
	v_pk_fma_f32 v[110:111], v[122:123], v[178:179], v[110:111]
	v_pk_fma_f32 v[100:101], v[100:101], v[180:181], v[118:119]
	v_cvt_pk_f32_fp8_e32 v[118:119], v102
	v_cvt_pk_f32_fp8_sdwa v[122:123], v102 src0_sel:WORD_1
	v_cvt_pk_f32_fp8_e32 v[126:127], v103
	v_cvt_pk_f32_fp8_sdwa v[102:103], v103 src0_sel:WORD_1
	v_pk_fma_f32 v[110:111], v[118:119], v[156:157], v[110:111]
	v_pk_fma_f32 v[100:101], v[122:123], v[152:153], v[100:101]
	v_pk_fma_f32 v[110:111], v[126:127], v[158:159], v[110:111]
	v_pk_fma_f32 v[100:101], v[102:103], v[154:155], v[100:101]
	v_cvt_pk_f32_fp8_e32 v[102:103], v96
	v_pk_add_f32 v[100:101], v[110:111], v[100:101]
	v_cvt_pk_f32_fp8_sdwa v[110:111], v96 src0_sel:WORD_1
	v_cvt_pk_f32_fp8_e32 v[118:119], v97
	v_cvt_pk_f32_fp8_sdwa v[96:97], v97 src0_sel:WORD_1
	v_pk_fma_f32 v[102:103], v[102:103], v[174:175], 0 op_sel_hi:[1,1,0]
	v_pk_fma_f32 v[110:111], v[110:111], v[176:177], 0 op_sel_hi:[1,1,0]
	v_pk_fma_f32 v[102:103], v[118:119], v[178:179], v[102:103]
	v_pk_fma_f32 v[96:97], v[96:97], v[180:181], v[110:111]
	v_cvt_pk_f32_fp8_e32 v[110:111], v98
	v_cvt_pk_f32_fp8_sdwa v[118:119], v98 src0_sel:WORD_1
	v_cvt_pk_f32_fp8_e32 v[122:123], v99
	v_cvt_pk_f32_fp8_sdwa v[98:99], v99 src0_sel:WORD_1
	v_pk_fma_f32 v[102:103], v[110:111], v[156:157], v[102:103]
	v_pk_fma_f32 v[96:97], v[118:119], v[152:153], v[96:97]
	v_pk_fma_f32 v[102:103], v[122:123], v[158:159], v[102:103]
	v_pk_fma_f32 v[96:97], v[98:99], v[154:155], v[96:97]
; DI void peer_u_phase(const Params& p) {
;     ...
;     for (int i = 0; i < 16; ++i) {
;       f32x2 aA = {0.f, 0.f}, aB = {0.f, 0.f};
; #pragma unroll
;       for (int j = 0; j < 4; ++j) {
;         const f32x2 lo = __builtin_amdgcn_cvt_pk_f32_fp8((int)r.u[i][j], false);
;         const f32x2 hi = __builtin_amdgcn_cvt_pk_f32_fp8((int)r.u[i][j], true);
;         aA = __builtin_elementwise_fma(lo, x2[2 * j], aA);
;         aB = __builtin_elementwise_fma(hi, x2[2 * j + 1], aB);
;       }
;       aA += aB;
;       pr[i] = aA[0] + aA[1];
;     }
	v_cvt_pk_f32_fp8_e32 v[98:99], v88
	v_pk_add_f32 v[96:97], v[102:103], v[96:97]
	v_cvt_pk_f32_fp8_sdwa v[102:103], v88 src0_sel:WORD_1
	v_cvt_pk_f32_fp8_e32 v[110:111], v89
	v_cvt_pk_f32_fp8_sdwa v[88:89], v89 src0_sel:WORD_1
	v_pk_fma_f32 v[98:99], v[98:99], v[174:175], 0 op_sel_hi:[1,1,0]
	v_pk_fma_f32 v[102:103], v[102:103], v[176:177], 0 op_sel_hi:[1,1,0]
	v_pk_fma_f32 v[98:99], v[110:111], v[178:179], v[98:99]
	v_pk_fma_f32 v[88:89], v[88:89], v[180:181], v[102:103]
	v_cvt_pk_f32_fp8_e32 v[102:103], v90
	v_cvt_pk_f32_fp8_sdwa v[110:111], v90 src0_sel:WORD_1
	v_cvt_pk_f32_fp8_e32 v[118:119], v91
	v_cvt_pk_f32_fp8_sdwa v[90:91], v91 src0_sel:WORD_1
	v_pk_fma_f32 v[98:99], v[102:103], v[156:157], v[98:99]
	v_pk_fma_f32 v[88:89], v[110:111], v[152:153], v[88:89]
	v_pk_fma_f32 v[98:99], v[118:119], v[158:159], v[98:99]
	v_pk_fma_f32 v[88:89], v[90:91], v[154:155], v[88:89]
	v_cvt_pk_f32_fp8_e32 v[90:91], v72
	v_pk_add_f32 v[88:89], v[98:99], v[88:89]
	v_cvt_pk_f32_fp8_sdwa v[98:99], v72 src0_sel:WORD_1
	v_cvt_pk_f32_fp8_e32 v[102:103], v73
	v_cvt_pk_f32_fp8_sdwa v[72:73], v73 src0_sel:WORD_1
	v_pk_fma_f32 v[90:91], v[90:91], v[174:175], 0 op_sel_hi:[1,1,0]
	v_pk_fma_f32 v[98:99], v[98:99], v[176:177], 0 op_sel_hi:[1,1,0]
	v_pk_fma_f32 v[90:91], v[102:103], v[178:179], v[90:91]
	v_pk_fma_f32 v[72:73], v[72:73], v[180:181], v[98:99]
	v_cvt_pk_f32_fp8_e32 v[98:99], v74
	v_cvt_pk_f32_fp8_sdwa v[102:103], v74 src0_sel:WORD_1
	v_cvt_pk_f32_fp8_e32 v[110:111], v75
	v_cvt_pk_f32_fp8_sdwa v[74:75], v75 src0_sel:WORD_1
	v_pk_fma_f32 v[90:91], v[98:99], v[156:157], v[90:91]
	v_pk_fma_f32 v[72:73], v[102:103], v[152:153], v[72:73]
	v_pk_fma_f32 v[90:91], v[110:111], v[158:159], v[90:91]
	v_pk_fma_f32 v[72:73], v[74:75], v[154:155], v[72:73]
	v_cvt_pk_f32_fp8_e32 v[74:75], v68
	v_pk_add_f32 v[72:73], v[90:91], v[72:73]
	v_cvt_pk_f32_fp8_sdwa v[90:91], v68 src0_sel:WORD_1
	v_cvt_pk_f32_fp8_e32 v[98:99], v69
	v_cvt_pk_f32_fp8_sdwa v[68:69], v69 src0_sel:WORD_1
	v_pk_fma_f32 v[74:75], v[74:75], v[174:175], 0 op_sel_hi:[1,1,0]
	v_pk_fma_f32 v[90:91], v[90:91], v[176:177], 0 op_sel_hi:[1,1,0]
	v_pk_fma_f32 v[74:75], v[98:99], v[178:179], v[74:75]
	v_pk_fma_f32 v[68:69], v[68:69], v[180:181], v[90:91]
	v_cvt_pk_f32_fp8_e32 v[90:91], v70
	v_cvt_pk_f32_fp8_sdwa v[98:99], v70 src0_sel:WORD_1
	v_cvt_pk_f32_fp8_e32 v[102:103], v71
	v_cvt_pk_f32_fp8_sdwa v[70:71], v71 src0_sel:WORD_1
	v_pk_fma_f32 v[74:75], v[90:91], v[156:157], v[74:75]
	v_pk_fma_f32 v[68:69], v[98:99], v[152:153], v[68:69]
	v_pk_fma_f32 v[74:75], v[102:103], v[158:159], v[74:75]
	v_pk_fma_f32 v[68:69], v[70:71], v[154:155], v[68:69]
	v_cvt_pk_f32_fp8_e32 v[70:71], v64
	v_pk_add_f32 v[68:69], v[74:75], v[68:69]
	v_cvt_pk_f32_fp8_sdwa v[74:75], v64 src0_sel:WORD_1
	v_cvt_pk_f32_fp8_e32 v[90:91], v65
	v_cvt_pk_f32_fp8_sdwa v[64:65], v65 src0_sel:WORD_1
	v_pk_fma_f32 v[70:71], v[70:71], v[174:175], 0 op_sel_hi:[1,1,0]
	v_pk_fma_f32 v[74:75], v[74:75], v[176:177], 0 op_sel_hi:[1,1,0]
	v_pk_fma_f32 v[70:71], v[90:91], v[178:179], v[70:71]
	v_pk_fma_f32 v[64:65], v[64:65], v[180:181], v[74:75]
	v_cvt_pk_f32_fp8_e32 v[74:75], v66
	v_cvt_pk_f32_fp8_sdwa v[90:91], v66 src0_sel:WORD_1
	v_cvt_pk_f32_fp8_e32 v[98:99], v67
	v_cvt_pk_f32_fp8_sdwa v[66:67], v67 src0_sel:WORD_1
	v_pk_fma_f32 v[70:71], v[74:75], v[156:157], v[70:71]
	v_pk_fma_f32 v[64:65], v[90:91], v[152:153], v[64:65]
	v_pk_fma_f32 v[70:71], v[98:99], v[158:159], v[70:71]
	v_pk_fma_f32 v[64:65], v[66:67], v[154:155], v[64:65]
	v_cvt_pk_f32_fp8_e32 v[66:67], v56
	v_pk_add_f32 v[64:65], v[70:71], v[64:65]
	v_cvt_pk_f32_fp8_sdwa v[70:71], v56 src0_sel:WORD_1
	v_cvt_pk_f32_fp8_e32 v[74:75], v57
	v_cvt_pk_f32_fp8_sdwa v[56:57], v57 src0_sel:WORD_1
	v_pk_fma_f32 v[66:67], v[66:67], v[174:175], 0 op_sel_hi:[1,1,0]
	v_pk_fma_f32 v[70:71], v[70:71], v[176:177], 0 op_sel_hi:[1,1,0]
	v_pk_fma_f32 v[66:67], v[74:75], v[178:179], v[66:67]
	v_pk_fma_f32 v[56:57], v[56:57], v[180:181], v[70:71]
	v_cvt_pk_f32_fp8_e32 v[70:71], v58
	v_cvt_pk_f32_fp8_sdwa v[74:75], v58 src0_sel:WORD_1
	v_cvt_pk_f32_fp8_e32 v[90:91], v59
	v_cvt_pk_f32_fp8_sdwa v[58:59], v59 src0_sel:WORD_1
	v_pk_fma_f32 v[66:67], v[70:71], v[156:157], v[66:67]
	v_pk_fma_f32 v[56:57], v[74:75], v[152:153], v[56:57]
	v_pk_fma_f32 v[66:67], v[90:91], v[158:159], v[66:67]
	v_pk_fma_f32 v[56:57], v[58:59], v[154:155], v[56:57]
	v_cvt_pk_f32_fp8_e32 v[58:59], v48
	v_pk_add_f32 v[56:57], v[66:67], v[56:57]
	v_cvt_pk_f32_fp8_sdwa v[66:67], v48 src0_sel:WORD_1
	v_cvt_pk_f32_fp8_e32 v[70:71], v49
	v_cvt_pk_f32_fp8_sdwa v[48:49], v49 src0_sel:WORD_1
	v_pk_fma_f32 v[58:59], v[58:59], v[174:175], 0 op_sel_hi:[1,1,0]
	v_pk_fma_f32 v[66:67], v[66:67], v[176:177], 0 op_sel_hi:[1,1,0]
	v_pk_fma_f32 v[58:59], v[70:71], v[178:179], v[58:59]
	v_pk_fma_f32 v[48:49], v[48:49], v[180:181], v[66:67]
	v_cvt_pk_f32_fp8_e32 v[66:67], v50
	v_cvt_pk_f32_fp8_sdwa v[70:71], v50 src0_sel:WORD_1
	v_cvt_pk_f32_fp8_e32 v[74:75], v51
	v_cvt_pk_f32_fp8_sdwa v[50:51], v51 src0_sel:WORD_1
	v_pk_fma_f32 v[58:59], v[66:67], v[156:157], v[58:59]
; DI void peer_u_phase(const Params& p) {
;     ...
;     for (int i = 0; i < 16; ++i) {
;       f32x2 aA = {0.f, 0.f}, aB = {0.f, 0.f};
; #pragma unroll
;       for (int j = 0; j < 4; ++j) {
;         const f32x2 lo = __builtin_amdgcn_cvt_pk_f32_fp8((int)r.u[i][j], false);
;         const f32x2 hi = __builtin_amdgcn_cvt_pk_f32_fp8((int)r.u[i][j], true);
;         aA = __builtin_elementwise_fma(lo, x2[2 * j], aA);
;         aB = __builtin_elementwise_fma(hi, x2[2 * j + 1], aB);
;       }
;       aA += aB;
;       pr[i] = aA[0] + aA[1];
;     }
;     float r8[8], r4[4], r2[2];
; #pragma unroll
;     for (int k = 0; k < 8; ++k) {
;       const float keep = (lane & 4) ? pr[k + 8] : pr[k], send = (lane & 4) ? pr[k] : pr[k + 8];
;       r8[k] = keep + __shfl_xor(send, 4);
;     }
; #pragma unroll
;     for (int k = 0; k < 4; ++k) {
;       const float keep = (lane & 2) ? r8[k + 4] : r8[k], send = (lane & 2) ? r8[k] : r8[k + 4];
;       r4[k] = keep + __shfl_xor(send, 2);
;     }
; #pragma unroll
;     for (int k = 0; k < 2; ++k) {
;       const float keep = (lane & 1) ? r4[k + 2] : r4[k], send = (lane & 1) ? r4[k] : r4[k + 2];
;       r2[k] = keep + __shfl_xor(send, 1);
;     }
;     *(float2*)(PART + (size_t)tok * 128 + 2 * lane) = make_float2(r2[0], r2[1]);
	v_pk_fma_f32 v[48:49], v[70:71], v[152:153], v[48:49]
	v_pk_fma_f32 v[58:59], v[74:75], v[158:159], v[58:59]
	v_pk_fma_f32 v[48:49], v[50:51], v[154:155], v[48:49]
	v_cvt_pk_f32_fp8_e32 v[50:51], v44
	v_pk_add_f32 v[48:49], v[58:59], v[48:49]
	v_cvt_pk_f32_fp8_sdwa v[58:59], v44 src0_sel:WORD_1
	v_cvt_pk_f32_fp8_e32 v[66:67], v45
	v_cvt_pk_f32_fp8_sdwa v[44:45], v45 src0_sel:WORD_1
	v_pk_fma_f32 v[50:51], v[50:51], v[174:175], 0 op_sel_hi:[1,1,0]
	v_pk_fma_f32 v[58:59], v[58:59], v[176:177], 0 op_sel_hi:[1,1,0]
	v_pk_fma_f32 v[50:51], v[66:67], v[178:179], v[50:51]
	v_pk_fma_f32 v[44:45], v[44:45], v[180:181], v[58:59]
	v_cvt_pk_f32_fp8_e32 v[58:59], v46
	v_cvt_pk_f32_fp8_sdwa v[66:67], v46 src0_sel:WORD_1
	v_cvt_pk_f32_fp8_e32 v[70:71], v47
	v_cvt_pk_f32_fp8_sdwa v[46:47], v47 src0_sel:WORD_1
	v_pk_fma_f32 v[50:51], v[58:59], v[156:157], v[50:51]
	v_pk_fma_f32 v[44:45], v[66:67], v[152:153], v[44:45]
	v_pk_fma_f32 v[50:51], v[70:71], v[158:159], v[50:51]
	v_pk_fma_f32 v[44:45], v[46:47], v[154:155], v[44:45]
	v_cvt_pk_f32_fp8_e32 v[46:47], v36
	v_pk_add_f32 v[44:45], v[50:51], v[44:45]
	v_cvt_pk_f32_fp8_sdwa v[50:51], v36 src0_sel:WORD_1
	v_cvt_pk_f32_fp8_e32 v[58:59], v37
	v_cvt_pk_f32_fp8_sdwa v[36:37], v37 src0_sel:WORD_1
	v_pk_fma_f32 v[46:47], v[46:47], v[174:175], 0 op_sel_hi:[1,1,0]
	v_pk_fma_f32 v[50:51], v[50:51], v[176:177], 0 op_sel_hi:[1,1,0]
	v_pk_fma_f32 v[46:47], v[58:59], v[178:179], v[46:47]
	v_pk_fma_f32 v[36:37], v[36:37], v[180:181], v[50:51]
	v_cvt_pk_f32_fp8_e32 v[50:51], v38
	v_cvt_pk_f32_fp8_sdwa v[58:59], v38 src0_sel:WORD_1
	v_cvt_pk_f32_fp8_e32 v[66:67], v39
	v_cvt_pk_f32_fp8_sdwa v[38:39], v39 src0_sel:WORD_1
	v_pk_fma_f32 v[46:47], v[50:51], v[156:157], v[46:47]
	v_pk_fma_f32 v[36:37], v[58:59], v[152:153], v[36:37]
	v_pk_fma_f32 v[46:47], v[66:67], v[158:159], v[46:47]
	v_pk_fma_f32 v[36:37], v[38:39], v[154:155], v[36:37]
	v_mov_b32_e32 v38, v132
	v_pk_add_f32 v[36:37], v[46:47], v[36:37]
	v_mov_b32_e32 v39, v128
	v_mov_b32_e32 v128, v133
	v_mov_b32_e32 v66, v88
	v_mov_b32_e32 v67, v72
	v_mov_b32_e32 v72, v89
	v_pk_add_f32 v[38:39], v[38:39], v[128:129]
	v_pk_add_f32 v[66:67], v[66:67], v[72:73]
	v_mov_b32_e32 v70, v68
	v_mov_b32_e32 v71, v64
	v_mov_b32_e32 v64, v69
	v_mov_b32_e32 v68, v56
	v_mov_b32_e32 v69, v48
	v_mov_b32_e32 v48, v57
	v_mov_b32_e32 v56, v44
	v_mov_b32_e32 v57, v36
	v_mov_b32_e32 v36, v45
	v_pk_add_f32 v[36:37], v[56:57], v[36:37]
	v_cndmask_b32_e32 v44, v38, v66, vcc
	v_cndmask_b32_e32 v57, v67, v39, vcc
	v_cndmask_b32_e32 v39, v39, v67, vcc
	ds_bpermute_b32 v44, v161, v44
	ds_bpermute_b32 v45, v161, v39
	v_mov_b32_e32 v46, v124
	v_mov_b32_e32 v47, v120
	v_mov_b32_e32 v120, v125
	v_pk_add_f32 v[46:47], v[46:47], v[120:121]
	v_pk_add_f32 v[64:65], v[70:71], v[64:65]
	v_mov_b32_e32 v50, v116
	v_mov_b32_e32 v51, v108
	v_mov_b32_e32 v108, v117
	v_mov_b32_e32 v58, v100
	v_mov_b32_e32 v59, v96
	v_mov_b32_e32 v96, v101
	v_cndmask_b32_e32 v39, v46, v64, vcc
	v_pk_add_f32 v[50:51], v[50:51], v[108:109]
	v_pk_add_f32 v[58:59], v[58:59], v[96:97]
	v_pk_add_f32 v[48:49], v[68:69], v[48:49]
	ds_bpermute_b32 v68, v161, v39
	v_cndmask_b32_e32 v39, v47, v65, vcc
	v_cndmask_b32_e32 v56, v66, v38, vcc
	ds_bpermute_b32 v69, v161, v39
	s_waitcnt lgkmcnt(2)
	v_pk_add_f32 v[38:39], v[56:57], v[44:45]
	v_cndmask_b32_e32 v45, v65, v47, vcc
	v_cndmask_b32_e32 v44, v64, v46, vcc
	v_cndmask_b32_e32 v46, v50, v48, vcc
	v_cndmask_b32_e32 v57, v49, v51, vcc
	v_cndmask_b32_e32 v47, v51, v49, vcc
	v_cndmask_b32_e32 v49, v58, v36, vcc
	ds_bpermute_b32 v46, v161, v46
	ds_bpermute_b32 v47, v161, v47
	ds_bpermute_b32 v64, v161, v49
	v_cndmask_b32_e32 v49, v59, v37, vcc
	ds_bpermute_b32 v65, v161, v49
	v_cndmask_b32_e32 v56, v48, v50, vcc
	s_waitcnt lgkmcnt(2)
	v_pk_add_f32 v[46:47], v[56:57], v[46:47]
	v_cndmask_b32_e32 v37, v37, v59, vcc
	v_cndmask_b32_e32 v36, v36, v58, vcc
	v_pk_add_f32 v[44:45], v[44:45], v[68:69]
	s_waitcnt lgkmcnt(0)
	v_pk_add_f32 v[36:37], v[36:37], v[64:65]
	v_cndmask_b32_e64 v51, v47, v39, s[4:5]
	v_cndmask_b32_e64 v39, v39, v47, s[4:5]
	ds_bpermute_b32 v49, v184, v39
	v_cndmask_b32_e64 v39, v44, v36, s[4:5]
	v_cndmask_b32_e64 v48, v38, v46, s[4:5]
	ds_bpermute_b32 v56, v184, v39
	v_cndmask_b32_e64 v39, v45, v37, s[4:5]
	ds_bpermute_b32 v48, v184, v48
	ds_bpermute_b32 v57, v184, v39
	v_cndmask_b32_e64 v50, v46, v38, s[4:5]
	v_cndmask_b32_e64 v37, v37, v45, s[4:5]
	v_cndmask_b32_e64 v36, v36, v44, s[4:5]
	s_waitcnt lgkmcnt(1)
	v_pk_add_f32 v[38:39], v[50:51], v[48:49]
	s_waitcnt lgkmcnt(0)
	v_pk_add_f32 v[36:37], v[36:37], v[56:57]
	v_lshlrev_b64 v[46:47], 9, v[172:173]
	v_cndmask_b32_e64 v44, v38, v36, s[6:7]
	v_cndmask_b32_e64 v45, v39, v37, s[6:7]
	ds_bpermute_b32 v44, v185, v44
	ds_bpermute_b32 v45, v185, v45
	v_cndmask_b32_e64 v37, v37, v39, s[6:7]
	v_cndmask_b32_e64 v36, v36, v38, s[6:7]
	v_lshl_add_u64 v[46:47], v[168:169], 0, v[46:47]
	s_waitcnt lgkmcnt(0)
	v_pk_add_f32 v[36:37], v[36:37], v[44:45]
	global_store_dwordx2 v[46:47], v[36:37], off
	s_branch .LBB0_1354

; DI int otid() { int t = threadIdx.x; asm volatile("" : "+v"(t)); return t; }
; DI void peer_v_phase(const Params& p) {
;   const int tid_ = otid();
;   const int lane = tid_ & 63, wave = tid_ >> 6;
;   const int g = blockIdx.x & 7, rank = blockIdx.x >> 3, nrank = gridDim.x >> 3;
;   if (rank >= nrank) return;
;   const int q = lane >> 3, s = lane & 7;
;   const unsigned char* Vb = (const unsigned char*)(p.ws + OFF_VB) + (size_t)g * (16384 * 128) + 16 * s;
;   const int* EID = (const int*)(p.ws + OFF_EID);
;   const float* W = (const float*)(p.ws + OFF_W);
;   float* SSP = (float*)(p.ws + OFF_SSP) + (size_t)g * T_TOK;
;   const int first = rank * 4 + wave, stride = nrank * 4;
;   const int n = (T_TOK - first + stride - 1) / stride;
;   auto tokof = [&](int k) { return first + (k < n ? k : n - 1) * stride; };
.LBB0_1473:
	s_or_b64 exec, exec, s[4:5]
	v_mov_b32_e32 v62, v192
	s_andn2_b64 vcc, exec, s[10:11]
	s_waitcnt lgkmcnt(0)
	s_barrier
	s_cbranch_vccnz .LBB0_1483
	s_lshl_b32 s18, s0, 2
	v_cvt_f32_u32_e32 v0, s18
	v_ashrrev_i32_e32 v1, 6, v62
	v_lshl_add_u32 v194, s1, 2, v1
	v_sub_u32_e32 v1, s18, v194
	v_rcp_iflag_f32_e32 v0, v0
	v_add_u32_e32 v1, 0x3fff, v1
	s_sub_i32 s1, 0, s18
	v_sub_u32_e32 v3, 0, v1
	v_mul_f32_e32 v0, 0x4f7ffffe, v0
	v_cvt_u32_f32_e32 v0, v0
	v_ashrrev_i32_e32 v2, 31, v1
	v_max_i32_e32 v1, v1, v3
	v_mul_lo_u32 v3, s1, v0
	v_mul_hi_u32 v3, v0, v3
	v_add_u32_e32 v0, v0, v3
	v_mul_hi_u32 v0, v1, v0
	v_mul_lo_u32 v3, v0, s18
	v_sub_u32_e32 v1, v1, v3
	v_add_u32_e32 v4, 1, v0
	v_cmp_le_u32_e32 vcc, s18, v1
	v_subrev_u32_e32 v3, s18, v1
	s_nop 0
	v_cndmask_b32_e32 v0, v0, v4, vcc
	v_cndmask_b32_e32 v1, v1, v3, vcc
	v_add_u32_e32 v3, 1, v0
	v_cmp_le_u32_e32 vcc, s18, v1
	s_nop 1
	v_cndmask_b32_e32 v0, v0, v3, vcc
	v_xor_b32_e32 v0, v0, v2
	v_sub_u32_e32 v193, v0, v2
	v_cmp_lt_i32_e32 vcc, 0, v193
	s_and_saveexec_b64 s[10:11], vcc
	s_cbranch_execz .LBB0_1482
; DI void peer_v_phase(const Params& p) {
;     ...
;   const int g = blockIdx.x & 7, rank = blockIdx.x >> 3, nrank = gridDim.x >> 3;
;   if (rank >= nrank) return;
;   const int q = lane >> 3, s = lane & 7;
;   const unsigned char* Vb = (const unsigned char*)(p.ws + OFF_VB) + (size_t)g * (16384 * 128) + 16 * s;
;   const int* EID = (const int*)(p.ws + OFF_EID);
;   const float* W = (const float*)(p.ws + OFF_W);
;   float* SSP = (float*)(p.ws + OFF_SSP) + (size_t)g * T_TOK;
;   const int first = rank * 4 + wave, stride = nrank * 4;
;   const int n = (T_TOK - first + stride - 1) / stride;
;   auto tokof = [&](int k) { return first + (k < n ? k : n - 1) * stride; };
;   auto gather = [&](PeerVRows& r, const int* e, int tok) {
; #pragma unroll
;     for (int i = 0; i < 16; ++i) r.v[i] = *(const u32x4*)(Vb + (size_t)e[i] * 128);
;     const float4* wp = (const float4*)(W + (size_t)tok * 128 + 16 * q);
; #pragma unroll
;     for (int j = 0; j < 4; ++j) r.w[j] = wp[j];
;   };
;     ...
;   int ea[16], eb[16];
;   PeerVRows ga, gb;
;   peer_load_e(ea, EID, tokof(0), q);
;   peer_load_e(eb, EID, tokof(1), q);
;   gather(ga, ea, tokof(0));
	v_lshlrev_b32_e32 v0, 3, v62
	v_ashrrev_i32_e32 v195, 31, v194
	v_mov_b32_e32 v61, 0
	v_and_b32_e32 v72, 0x1c0, v0
	v_lshlrev_b64 v[0:1], 9, v[194:195]
	v_mov_b32_e32 v73, v61
	v_lshl_add_u64 v[2:3], s[86:87], 0, v[0:1]
	v_lshl_add_u64 v[2:3], v[2:3], 0, v[72:73]
	global_load_dwordx4 v[4:7], v[2:3], off offset:48
	global_load_dwordx4 v[8:11], v[2:3], off offset:32
	global_load_dwordx4 v[16:19], v[2:3], off offset:16
	global_load_dwordx4 v[68:71], v[2:3], off
	s_and_b32 s8, s80, 7
	s_lshl_b32 s1, s8, 21
	v_lshlrev_b32_e32 v2, 4, v62
	s_add_u32 s2, s86, s1
	v_and_b32_e32 v60, 0x70, v2
	s_addc_u32 s3, s87, 0
	v_lshl_add_u64 v[2:3], s[2:3], 0, v[60:61]
	s_add_u32 s2, s86, 0x5000000
	s_addc_u32 s3, s87, 0
	v_lshl_add_u64 v[0:1], s[2:3], 0, v[0:1]
	s_mov_b64 s[4:5], 0x9000000
	v_lshl_add_u64 v[20:21], v[0:1], 0, v[72:73]
	v_lshl_add_u64 v[196:197], v[2:3], 0, s[4:5]
	global_load_dwordx4 v[0:3], v[20:21], off offset:48
	global_load_dwordx4 v[12:15], v[20:21], off offset:32
	global_load_dwordx4 v[28:31], v[20:21], off offset:16
	global_load_dwordx4 v[52:55], v[20:21], off
	v_add_u32_e32 v195, -1, v193
	v_mov_b32_e32 v63, s18
	v_cmp_ne_u32_e32 vcc, 0, v195
	s_lshl_b32 s1, s8, 16
	v_lshl_add_u64 v[200:201], s[2:3], 0, v[72:73]
	v_cndmask_b32_e32 v63, 0, v63, vcc
	s_add_u32 s1, s86, s1
	s_addc_u32 s4, s87, 0
	s_add_u32 s12, s1, 0x5800000
	s_addc_u32 s13, s4, 0
	s_lshl_b32 s8, s8, 9
	s_add_u32 s8, s84, s8
	s_addc_u32 s9, s85, 0
	v_lshlrev_b32_e32 v60, 2, v60
	s_mov_b32 s1, 3
	v_lshl_add_u64 v[198:199], s[86:87], 0, v[72:73]
	s_lshl_b32 s0, s0, 3
	s_mov_b64 s[14:15], 0
	v_mov_b32_e32 v204, v194
	s_waitcnt vmcnt(7)
	v_ashrrev_i32_e32 v21, 31, v7
	v_mov_b32_e32 v20, v7
	v_ashrrev_i32_e32 v7, 31, v6
	v_ashrrev_i32_e32 v23, 31, v5
	v_mov_b32_e32 v22, v5
	v_ashrrev_i32_e32 v5, 31, v4
	s_waitcnt vmcnt(4)
	v_ashrrev_i32_e32 v75, 31, v71
	v_mov_b32_e32 v74, v71
	v_ashrrev_i32_e32 v71, 31, v70
	v_ashrrev_i32_e32 v25, 31, v11
	v_mov_b32_e32 v24, v11
	v_ashrrev_i32_e32 v11, 31, v10
	v_ashrrev_i32_e32 v27, 31, v9
	v_mov_b32_e32 v26, v9
	v_ashrrev_i32_e32 v9, 31, v8
	v_ashrrev_i32_e32 v33, 31, v19
	v_mov_b32_e32 v32, v19
	v_ashrrev_i32_e32 v19, 31, v18
	v_ashrrev_i32_e32 v35, 31, v17
	v_mov_b32_e32 v34, v17
	v_ashrrev_i32_e32 v17, 31, v16
	v_lshlrev_b64 v[6:7], 7, v[6:7]
	v_lshlrev_b64 v[20:21], 7, v[20:21]
	v_lshlrev_b64 v[4:5], 7, v[4:5]
	v_lshlrev_b64 v[22:23], 7, v[22:23]
	v_lshlrev_b64 v[70:71], 7, v[70:71]
	v_lshlrev_b64 v[74:75], 7, v[74:75]
	v_lshlrev_b64 v[10:11], 7, v[10:11]
	v_lshlrev_b64 v[24:25], 7, v[24:25]
	v_lshlrev_b64 v[8:9], 7, v[8:9]
	v_lshlrev_b64 v[26:27], 7, v[26:27]
	v_lshlrev_b64 v[18:19], 7, v[18:19]
	v_lshlrev_b64 v[32:33], 7, v[32:33]
	v_lshlrev_b64 v[16:17], 7, v[16:17]
	v_lshlrev_b64 v[34:35], 7, v[34:35]
	v_lshl_add_u64 v[76:77], v[196:197], 0, v[20:21]
	v_lshl_add_u64 v[78:79], v[196:197], 0, v[6:7]
	v_lshl_add_u64 v[80:81], v[196:197], 0, v[22:23]
	v_lshl_add_u64 v[82:83], v[196:197], 0, v[4:5]
	v_lshl_add_u64 v[74:75], v[196:197], 0, v[74:75]
	v_lshl_add_u64 v[70:71], v[196:197], 0, v[70:71]
	v_lshl_add_u64 v[84:85], v[196:197], 0, v[24:25]
	v_lshl_add_u64 v[86:87], v[196:197], 0, v[10:11]
	v_lshl_add_u64 v[88:89], v[196:197], 0, v[26:27]
	v_lshl_add_u64 v[90:91], v[196:197], 0, v[8:9]
	v_lshl_add_u64 v[92:93], v[196:197], 0, v[32:33]
	v_lshl_add_u64 v[94:95], v[196:197], 0, v[18:19]
	v_lshl_add_u64 v[96:97], v[196:197], 0, v[34:35]
	v_lshl_add_u64 v[98:99], v[196:197], 0, v[16:17]
	global_load_dwordx4 v[4:7], v[76:77], off
	global_load_dwordx4 v[8:11], v[78:79], off
	global_load_dwordx4 v[16:19], v[80:81], off
	global_load_dwordx4 v[20:23], v[82:83], off
	global_load_dwordx4 v[24:27], v[84:85], off
	global_load_dwordx4 v[32:35], v[86:87], off
	global_load_dwordx4 v[36:39], v[88:89], off
	global_load_dwordx4 v[40:43], v[90:91], off
	global_load_dwordx4 v[44:47], v[92:93], off
	global_load_dwordx4 v[48:51], v[94:95], off
	global_load_dwordx4 v[56:59], v[96:97], off
	global_load_dwordx4 v[64:67], v[98:99], off
	global_load_dwordx4 v[76:79], v[74:75], off
	global_load_dwordx4 v[80:83], v[70:71], off
	v_ashrrev_i32_e32 v71, 31, v69
	v_mov_b32_e32 v70, v69
	v_ashrrev_i32_e32 v69, 31, v68
	v_lshlrev_b64 v[68:69], 7, v[68:69]
	v_lshlrev_b64 v[70:71], 7, v[70:71]
	v_lshl_add_u64 v[70:71], v[196:197], 0, v[70:71]
	v_lshl_add_u64 v[68:69], v[196:197], 0, v[68:69]
	global_load_dwordx4 v[84:87], v[70:71], off
	global_load_dwordx4 v[88:91], v[68:69], off
	v_add_u32_e32 v68, v63, v194
	v_ashrrev_i32_e32 v69, 31, v68
	v_lshlrev_b64 v[68:69], 9, v[68:69]
	v_lshl_add_u64 v[68:69], s[86:87], 0, v[68:69]
	v_lshl_add_u64 v[68:69], v[68:69], 0, v[72:73]
	global_load_dwordx4 v[96:99], v[68:69], off offset:48
	global_load_dwordx4 v[108:111], v[68:69], off offset:32
	global_load_dwordx4 v[116:119], v[68:69], off offset:16
	global_load_dwordx4 v[132:135], v[68:69], off
	v_and_b32_e32 v68, 32, v62
	v_cmp_eq_u32_e32 vcc, 0, v68
	v_mbcnt_lo_u32_b32 v68, -1, 0
	v_mbcnt_hi_u32_b32 v68, -1, v68
	v_and_b32_e32 v70, 64, v68
	v_xor_b32_e32 v69, 32, v68
	v_add_u32_e32 v70, 64, v70
	v_cmp_lt_i32_e64 s[2:3], v69, v70
	v_and_b32_e32 v63, 63, v62
	s_nop 0
	v_cndmask_b32_e64 v69, v68, v69, s[2:3]
	v_lshlrev_b32_e32 v210, 2, v69
	v_and_b32_e32 v69, 16, v62
	v_cmp_eq_u32_e64 s[2:3], 0, v69
	v_xor_b32_e32 v69, 16, v68
	v_cmp_lt_i32_e64 s[4:5], v69, v70
	s_nop 1
	v_cndmask_b32_e64 v69, v68, v69, s[4:5]
	v_lshlrev_b32_e32 v211, 2, v69
	v_and_b32_e32 v69, 8, v62
	v_cmp_eq_u32_e64 s[4:5], 0, v69
	v_xor_b32_e32 v69, 8, v68
	v_cmp_lt_i32_e64 s[6:7], v69, v70
	s_nop 1
	v_cndmask_b32_e64 v69, v68, v69, s[6:7]
	v_lshlrev_b32_e32 v212, 2, v69
	v_xor_b32_e32 v69, 4, v68
	v_cmp_lt_i32_e64 s[6:7], v69, v70
	s_nop 1
	v_cndmask_b32_e64 v69, v68, v69, s[6:7]
	v_lshlrev_b32_e32 v213, 2, v69
	v_xor_b32_e32 v69, 2, v68
	v_cmp_lt_i32_e64 s[6:7], v69, v70
	s_nop 1
	v_cndmask_b32_e64 v69, v68, v69, s[6:7]
	v_lshlrev_b32_e32 v214, 2, v69
	v_xor_b32_e32 v69, 1, v68
	v_cmp_lt_i32_e64 s[6:7], v69, v70
	s_nop 1
	v_cndmask_b32_e64 v68, v68, v69, s[6:7]
	v_lshlrev_b32_e32 v215, 2, v68
	v_lshl_add_u64 v[68:69], s[8:9], 0, v[60:61]
	v_and_b32_e32 v60, 56, v62
	v_cmp_eq_u32_e64 s[6:7], 63, v63
	v_lshl_add_u64 v[202:203], v[68:69], 0, v[60:61]
	s_waitcnt vmcnt(0)
	s_branch .LBB0_1477

; DI void peer_v_phase(const Params& p) {
;     ...
;   auto gather = [&](PeerVRows& r, const int* e, int tok) {
; #pragma unroll
;     for (int i = 0; i < 16; ++i) r.v[i] = *(const u32x4*)(Vb + (size_t)e[i] * 128);
;     const float4* wp = (const float4*)(W + (size_t)tok * 128 + 16 * q);
; #pragma unroll
;     for (int j = 0; j < 4; ++j) r.w[j] = wp[j];
;   };
;   auto compute = [&](const PeerVRows& r, int tok) {
;     f32x2 o2[8];
; #pragma unroll
;     for (int k = 0; k < 8; ++k) { o2[k][0] = 0.f; o2[k][1] = 0.f; }
; #pragma unroll
;     for (int i = 0; i < 16; ++i) {
;       const float wi = (i & 3) == 0 ? r.w[i >> 2].x : (i & 3) == 1 ? r.w[i >> 2].y : (i & 3) == 2 ? r.w[i >> 2].z : r.w[i >> 2].w;
;       const f32x2 w2 = {wi, wi};
; #pragma unroll
;       for (int j = 0; j < 4; ++j) {
;         const f32x2 lo = __builtin_amdgcn_cvt_pk_f32_fp8((int)r.v[i][j], false);
;         const f32x2 hi = __builtin_amdgcn_cvt_pk_f32_fp8((int)r.v[i][j], true);
;         o2[2 * j] = __builtin_elementwise_fma(lo, w2, o2[2 * j]);
;         o2[2 * j + 1] = __builtin_elementwise_fma(hi, w2, o2[2 * j + 1]);
;       }
;     }
;     ...
;   for (int k = 0; k < n; k += 2) {
;     peer_load_e(ea, EID, tokof(k + 2), q);
;     gather(gb, eb, tokof(k + 1));
;     __builtin_amdgcn_sched_barrier(0);
;     compute(ga, tokof(k));
.LBB0_1477:
	s_add_i32 s19, s1, -1
	v_min_i32_e32 v60, s19, v195
	s_waitcnt lgkmcnt(0)
	v_mad_u64_u32 v[60:61], s[8:9], v60, s18, v[194:195]
	v_ashrrev_i32_e32 v61, 31, v60
	v_lshlrev_b64 v[208:209], 9, v[60:61]
	v_lshl_add_u64 v[60:61], v[198:199], 0, v[208:209]
	s_add_i32 s16, s1, -2
	global_load_dwordx4 v[172:175], v[60:61], off offset:48
	global_load_dwordx4 v[176:179], v[60:61], off offset:32
	global_load_dwordx4 v[184:187], v[60:61], off offset:16
	global_load_dwordx4 v[188:191], v[60:61], off
	v_ashrrev_i32_e32 v235, 31, v204
	v_mov_b32_e32 v234, v204
	v_lshlrev_b64 v[234:235], 12, v[234:235]
	v_lshl_add_u64 v[234:235], v[202:203], 0, v[234:235]
	global_load_dwordx2 v[232:233], v[234:235], off
	v_min_i32_e32 v60, s16, v195
	v_mad_u64_u32 v[206:207], s[8:9], v60, s18, v[194:195]
	s_waitcnt vmcnt(7)
	v_ashrrev_i32_e32 v61, 31, v132
	v_mov_b32_e32 v60, v132
	v_ashrrev_i32_e32 v63, 31, v133
	v_mov_b32_e32 v62, v133
	v_lshlrev_b64 v[60:61], 7, v[60:61]
	v_lshlrev_b64 v[62:63], 7, v[62:63]
	v_lshl_add_u64 v[60:61], v[196:197], 0, v[60:61]
	v_lshl_add_u64 v[62:63], v[196:197], 0, v[62:63]
	global_load_dwordx4 v[168:171], v[60:61], off
	global_load_dwordx4 v[164:167], v[62:63], off
	v_ashrrev_i32_e32 v61, 31, v134
	v_mov_b32_e32 v60, v134
	v_ashrrev_i32_e32 v63, 31, v135
	v_mov_b32_e32 v62, v135
	v_lshlrev_b64 v[60:61], 7, v[60:61]
	v_lshlrev_b64 v[62:63], 7, v[62:63]
	v_lshl_add_u64 v[60:61], v[196:197], 0, v[60:61]
	v_lshl_add_u64 v[62:63], v[196:197], 0, v[62:63]
	global_load_dwordx4 v[160:163], v[60:61], off
	global_load_dwordx4 v[152:155], v[62:63], off
	v_ashrrev_i32_e32 v61, 31, v116
	v_mov_b32_e32 v60, v116
	v_ashrrev_i32_e32 v63, 31, v117
	v_mov_b32_e32 v62, v117
	v_lshlrev_b64 v[60:61], 7, v[60:61]
	v_lshlrev_b64 v[62:63], 7, v[62:63]
	v_lshl_add_u64 v[60:61], v[196:197], 0, v[60:61]
	v_lshl_add_u64 v[62:63], v[196:197], 0, v[62:63]
	global_load_dwordx4 v[148:151], v[60:61], off
	global_load_dwordx4 v[144:147], v[62:63], off
	v_ashrrev_i32_e32 v61, 31, v118
	v_mov_b32_e32 v60, v118
	v_ashrrev_i32_e32 v63, 31, v119
	v_mov_b32_e32 v62, v119
	v_lshlrev_b64 v[60:61], 7, v[60:61]
	v_lshlrev_b64 v[62:63], 7, v[62:63]
	v_lshl_add_u64 v[60:61], v[196:197], 0, v[60:61]
	v_lshl_add_u64 v[62:63], v[196:197], 0, v[62:63]
	global_load_dwordx4 v[140:143], v[60:61], off
	global_load_dwordx4 v[136:139], v[62:63], off
	v_ashrrev_i32_e32 v61, 31, v108
	v_mov_b32_e32 v60, v108
	v_ashrrev_i32_e32 v63, 31, v109
	v_mov_b32_e32 v62, v109
	v_lshlrev_b64 v[60:61], 7, v[60:61]
	v_lshlrev_b64 v[62:63], 7, v[62:63]
	v_lshl_add_u64 v[60:61], v[196:197], 0, v[60:61]
	v_lshl_add_u64 v[62:63], v[196:197], 0, v[62:63]
	global_load_dwordx4 v[128:131], v[60:61], off
	global_load_dwordx4 v[120:123], v[62:63], off
	v_ashrrev_i32_e32 v61, 31, v110
	v_mov_b32_e32 v60, v110
	v_ashrrev_i32_e32 v63, 31, v111
	v_mov_b32_e32 v62, v111
	v_lshlrev_b64 v[60:61], 7, v[60:61]
	v_lshlrev_b64 v[62:63], 7, v[62:63]
	v_lshl_add_u64 v[60:61], v[196:197], 0, v[60:61]
	v_lshl_add_u64 v[62:63], v[196:197], 0, v[62:63]
	global_load_dwordx4 v[112:115], v[60:61], off
	global_load_dwordx4 v[104:107], v[62:63], off
	v_ashrrev_i32_e32 v61, 31, v96
	v_mov_b32_e32 v60, v96
	v_ashrrev_i32_e32 v63, 31, v97
	v_mov_b32_e32 v62, v97
	v_lshlrev_b64 v[60:61], 7, v[60:61]
	v_lshlrev_b64 v[62:63], 7, v[62:63]
	v_lshl_add_u64 v[60:61], v[196:197], 0, v[60:61]
	v_lshl_add_u64 v[62:63], v[196:197], 0, v[62:63]
	global_load_dwordx4 v[100:103], v[60:61], off
	global_load_dwordx4 v[92:95], v[62:63], off
	v_ashrrev_i32_e32 v61, 31, v98
	v_mov_b32_e32 v60, v98
	v_ashrrev_i32_e32 v63, 31, v99
	v_mov_b32_e32 v62, v99
	v_ashrrev_i32_e32 v207, 31, v206
	v_lshlrev_b64 v[60:61], 7, v[60:61]
	v_lshlrev_b64 v[62:63], 7, v[62:63]
	v_lshlrev_b64 v[72:73], 9, v[206:207]
	v_lshl_add_u64 v[60:61], v[196:197], 0, v[60:61]
	v_lshl_add_u64 v[62:63], v[196:197], 0, v[62:63]
	v_lshl_add_u64 v[96:97], v[200:201], 0, v[72:73]
	global_load_dwordx4 v[68:71], v[60:61], off
	s_nop 0
	global_load_dwordx4 v[60:63], v[62:63], off
	s_nop 0
	global_load_dwordx4 v[72:75], v[96:97], off offset:48
	global_load_dwordx4 v[124:127], v[96:97], off offset:32
	global_load_dwordx4 v[156:159], v[96:97], off offset:16
	global_load_dwordx4 v[180:183], v[96:97], off
	v_cvt_pk_f32_fp8_e32 v[96:97], v88
	v_cvt_pk_f32_fp8_sdwa v[98:99], v88 src0_sel:WORD_1
	v_cvt_pk_f32_fp8_e32 v[108:109], v89
	v_cvt_pk_f32_fp8_sdwa v[88:89], v89 src0_sel:WORD_1
	v_cvt_pk_f32_fp8_e32 v[132:133], v84
	v_cvt_pk_f32_fp8_sdwa v[134:135], v84 src0_sel:WORD_1
	v_cvt_pk_f32_fp8_e32 v[216:217], v85
	v_cvt_pk_f32_fp8_sdwa v[84:85], v85 src0_sel:WORD_1
	v_pk_fma_f32 v[96:97], v[96:97], v[52:53], 0 op_sel_hi:[1,0,0]
	v_pk_fma_f32 v[98:99], v[98:99], v[52:53], 0 op_sel_hi:[1,0,0]
	v_pk_fma_f32 v[88:89], v[88:89], v[52:53], 0 op_sel_hi:[1,0,0]
	v_cvt_pk_f32_fp8_e32 v[110:111], v90
	v_cvt_pk_f32_fp8_sdwa v[116:117], v90 src0_sel:WORD_1
	v_cvt_pk_f32_fp8_e32 v[118:119], v91
	v_cvt_pk_f32_fp8_sdwa v[90:91], v91 src0_sel:WORD_1
	v_pk_fma_f32 v[96:97], v[132:133], v[52:53], v[96:97] op_sel:[0,1,0]
	v_pk_fma_f32 v[98:99], v[134:135], v[52:53], v[98:99] op_sel:[0,1,0]
	v_pk_fma_f32 v[84:85], v[84:85], v[52:53], v[88:89] op_sel:[0,1,0]
	v_cvt_pk_f32_fp8_e32 v[88:89], v86
	v_cvt_pk_f32_fp8_sdwa v[132:133], v86 src0_sel:WORD_1
	v_cvt_pk_f32_fp8_e32 v[134:135], v87
	v_cvt_pk_f32_fp8_sdwa v[86:87], v87 src0_sel:WORD_1
	v_pk_fma_f32 v[108:109], v[108:109], v[52:53], 0 op_sel_hi:[1,0,0]
	v_pk_fma_f32 v[110:111], v[110:111], v[52:53], 0 op_sel_hi:[1,0,0]
	v_pk_fma_f32 v[116:117], v[116:117], v[52:53], 0 op_sel_hi:[1,0,0]
	v_pk_fma_f32 v[118:119], v[118:119], v[52:53], 0 op_sel_hi:[1,0,0]
; DI void peer_v_phase(const Params& p) {
;     ...
;     for (int i = 0; i < 16; ++i) {
;       const float wi = (i & 3) == 0 ? r.w[i >> 2].x : (i & 3) == 1 ? r.w[i >> 2].y : (i & 3) == 2 ? r.w[i >> 2].z : r.w[i >> 2].w;
;       const f32x2 w2 = {wi, wi};
; #pragma unroll
;       for (int j = 0; j < 4; ++j) {
;         const f32x2 lo = __builtin_amdgcn_cvt_pk_f32_fp8((int)r.v[i][j], false);
;         const f32x2 hi = __builtin_amdgcn_cvt_pk_f32_fp8((int)r.v[i][j], true);
;         o2[2 * j] = __builtin_elementwise_fma(lo, w2, o2[2 * j]);
;         o2[2 * j + 1] = __builtin_elementwise_fma(hi, w2, o2[2 * j + 1]);
;       }
;     }
	v_pk_fma_f32 v[90:91], v[90:91], v[52:53], 0 op_sel_hi:[1,0,0]
	v_pk_fma_f32 v[108:109], v[216:217], v[52:53], v[108:109] op_sel:[0,1,0]
	v_pk_fma_f32 v[88:89], v[88:89], v[52:53], v[110:111] op_sel:[0,1,0]
	v_pk_fma_f32 v[110:111], v[132:133], v[52:53], v[116:117] op_sel:[0,1,0]
	v_pk_fma_f32 v[116:117], v[134:135], v[52:53], v[118:119] op_sel:[0,1,0]
	v_pk_fma_f32 v[52:53], v[86:87], v[52:53], v[90:91] op_sel:[0,1,0]
	v_cvt_pk_f32_fp8_e32 v[86:87], v80
	v_cvt_pk_f32_fp8_sdwa v[90:91], v80 src0_sel:WORD_1
	v_cvt_pk_f32_fp8_e32 v[118:119], v81
	v_cvt_pk_f32_fp8_sdwa v[80:81], v81 src0_sel:WORD_1
	v_pk_fma_f32 v[86:87], v[86:87], v[54:55], v[96:97] op_sel_hi:[1,0,1]
	v_pk_fma_f32 v[90:91], v[90:91], v[54:55], v[98:99] op_sel_hi:[1,0,1]
	v_pk_fma_f32 v[96:97], v[118:119], v[54:55], v[108:109] op_sel_hi:[1,0,1]
	v_pk_fma_f32 v[80:81], v[80:81], v[54:55], v[84:85] op_sel_hi:[1,0,1]
	v_cvt_pk_f32_fp8_e32 v[84:85], v82
	v_cvt_pk_f32_fp8_sdwa v[98:99], v82 src0_sel:WORD_1
	v_cvt_pk_f32_fp8_e32 v[108:109], v83
	v_cvt_pk_f32_fp8_sdwa v[82:83], v83 src0_sel:WORD_1
	v_pk_fma_f32 v[84:85], v[84:85], v[54:55], v[88:89] op_sel_hi:[1,0,1]
	v_pk_fma_f32 v[88:89], v[98:99], v[54:55], v[110:111] op_sel_hi:[1,0,1]
	v_pk_fma_f32 v[98:99], v[108:109], v[54:55], v[116:117] op_sel_hi:[1,0,1]
	v_pk_fma_f32 v[52:53], v[82:83], v[54:55], v[52:53] op_sel_hi:[1,0,1]
	v_cvt_pk_f32_fp8_e32 v[82:83], v76
	v_cvt_pk_f32_fp8_sdwa v[108:109], v76 src0_sel:WORD_1
	v_cvt_pk_f32_fp8_e32 v[110:111], v77
	v_cvt_pk_f32_fp8_sdwa v[76:77], v77 src0_sel:WORD_1
	v_pk_fma_f32 v[82:83], v[82:83], v[54:55], v[86:87] op_sel:[0,1,0]
	v_pk_fma_f32 v[86:87], v[108:109], v[54:55], v[90:91] op_sel:[0,1,0]
	v_pk_fma_f32 v[90:91], v[110:111], v[54:55], v[96:97] op_sel:[0,1,0]
	v_pk_fma_f32 v[76:77], v[76:77], v[54:55], v[80:81] op_sel:[0,1,0]
	v_cvt_pk_f32_fp8_e32 v[80:81], v78
	v_cvt_pk_f32_fp8_sdwa v[96:97], v78 src0_sel:WORD_1
	v_cvt_pk_f32_fp8_e32 v[108:109], v79
	v_cvt_pk_f32_fp8_sdwa v[78:79], v79 src0_sel:WORD_1
	v_pk_fma_f32 v[80:81], v[80:81], v[54:55], v[84:85] op_sel:[0,1,0]
	v_pk_fma_f32 v[84:85], v[96:97], v[54:55], v[88:89] op_sel:[0,1,0]
	v_pk_fma_f32 v[88:89], v[108:109], v[54:55], v[98:99] op_sel:[0,1,0]
	v_pk_fma_f32 v[52:53], v[78:79], v[54:55], v[52:53] op_sel:[0,1,0]
	v_cvt_pk_f32_fp8_e32 v[54:55], v64
	v_cvt_pk_f32_fp8_sdwa v[78:79], v64 src0_sel:WORD_1
	v_cvt_pk_f32_fp8_e32 v[96:97], v65
	v_cvt_pk_f32_fp8_sdwa v[64:65], v65 src0_sel:WORD_1
	v_pk_fma_f32 v[54:55], v[54:55], v[28:29], v[82:83] op_sel_hi:[1,0,1]
	v_pk_fma_f32 v[78:79], v[78:79], v[28:29], v[86:87] op_sel_hi:[1,0,1]
	v_pk_fma_f32 v[82:83], v[96:97], v[28:29], v[90:91] op_sel_hi:[1,0,1]
	v_pk_fma_f32 v[64:65], v[64:65], v[28:29], v[76:77] op_sel_hi:[1,0,1]
	v_cvt_pk_f32_fp8_e32 v[76:77], v66
	v_cvt_pk_f32_fp8_sdwa v[86:87], v66 src0_sel:WORD_1
	v_cvt_pk_f32_fp8_e32 v[90:91], v67
	v_cvt_pk_f32_fp8_sdwa v[66:67], v67 src0_sel:WORD_1
	v_pk_fma_f32 v[76:77], v[76:77], v[28:29], v[80:81] op_sel_hi:[1,0,1]
	v_pk_fma_f32 v[80:81], v[86:87], v[28:29], v[84:85] op_sel_hi:[1,0,1]
	v_pk_fma_f32 v[84:85], v[90:91], v[28:29], v[88:89] op_sel_hi:[1,0,1]
	v_pk_fma_f32 v[52:53], v[66:67], v[28:29], v[52:53] op_sel_hi:[1,0,1]
	v_cvt_pk_f32_fp8_e32 v[66:67], v56
	v_cvt_pk_f32_fp8_sdwa v[86:87], v56 src0_sel:WORD_1
	v_cvt_pk_f32_fp8_e32 v[88:89], v57
	v_cvt_pk_f32_fp8_sdwa v[56:57], v57 src0_sel:WORD_1
	v_pk_fma_f32 v[54:55], v[66:67], v[28:29], v[54:55] op_sel:[0,1,0]
	v_pk_fma_f32 v[66:67], v[86:87], v[28:29], v[78:79] op_sel:[0,1,0]
	v_pk_fma_f32 v[78:79], v[88:89], v[28:29], v[82:83] op_sel:[0,1,0]
	v_pk_fma_f32 v[56:57], v[56:57], v[28:29], v[64:65] op_sel:[0,1,0]
	v_cvt_pk_f32_fp8_e32 v[64:65], v58
	v_cvt_pk_f32_fp8_sdwa v[82:83], v58 src0_sel:WORD_1
	v_cvt_pk_f32_fp8_e32 v[86:87], v59
	v_cvt_pk_f32_fp8_sdwa v[58:59], v59 src0_sel:WORD_1
	v_pk_fma_f32 v[64:65], v[64:65], v[28:29], v[76:77] op_sel:[0,1,0]
	v_pk_fma_f32 v[76:77], v[82:83], v[28:29], v[80:81] op_sel:[0,1,0]
	v_pk_fma_f32 v[80:81], v[86:87], v[28:29], v[84:85] op_sel:[0,1,0]
	v_pk_fma_f32 v[28:29], v[58:59], v[28:29], v[52:53] op_sel:[0,1,0]
	v_cvt_pk_f32_fp8_e32 v[52:53], v48
	v_cvt_pk_f32_fp8_sdwa v[58:59], v48 src0_sel:WORD_1
	v_cvt_pk_f32_fp8_e32 v[82:83], v49
	v_cvt_pk_f32_fp8_sdwa v[48:49], v49 src0_sel:WORD_1
	v_pk_fma_f32 v[52:53], v[52:53], v[30:31], v[54:55] op_sel_hi:[1,0,1]
	v_pk_fma_f32 v[54:55], v[58:59], v[30:31], v[66:67] op_sel_hi:[1,0,1]
	v_pk_fma_f32 v[58:59], v[82:83], v[30:31], v[78:79] op_sel_hi:[1,0,1]
	v_pk_fma_f32 v[48:49], v[48:49], v[30:31], v[56:57] op_sel_hi:[1,0,1]
	v_cvt_pk_f32_fp8_e32 v[56:57], v50
	v_cvt_pk_f32_fp8_sdwa v[66:67], v50 src0_sel:WORD_1
	v_cvt_pk_f32_fp8_e32 v[78:79], v51
	v_cvt_pk_f32_fp8_sdwa v[50:51], v51 src0_sel:WORD_1
	v_pk_fma_f32 v[56:57], v[56:57], v[30:31], v[64:65] op_sel_hi:[1,0,1]
	v_pk_fma_f32 v[64:65], v[66:67], v[30:31], v[76:77] op_sel_hi:[1,0,1]
	v_pk_fma_f32 v[66:67], v[78:79], v[30:31], v[80:81] op_sel_hi:[1,0,1]
	v_pk_fma_f32 v[28:29], v[50:51], v[30:31], v[28:29] op_sel_hi:[1,0,1]
	v_cvt_pk_f32_fp8_e32 v[50:51], v44
	v_cvt_pk_f32_fp8_sdwa v[76:77], v44 src0_sel:WORD_1
	v_cvt_pk_f32_fp8_e32 v[78:79], v45
	v_cvt_pk_f32_fp8_sdwa v[44:45], v45 src0_sel:WORD_1
	v_pk_fma_f32 v[50:51], v[50:51], v[30:31], v[52:53] op_sel:[0,1,0]
	v_pk_fma_f32 v[52:53], v[76:77], v[30:31], v[54:55] op_sel:[0,1,0]
	v_pk_fma_f32 v[54:55], v[78:79], v[30:31], v[58:59] op_sel:[0,1,0]
	v_pk_fma_f32 v[44:45], v[44:45], v[30:31], v[48:49] op_sel:[0,1,0]
	v_cvt_pk_f32_fp8_e32 v[48:49], v46
	v_cvt_pk_f32_fp8_sdwa v[58:59], v46 src0_sel:WORD_1
	v_cvt_pk_f32_fp8_e32 v[76:77], v47
	v_cvt_pk_f32_fp8_sdwa v[46:47], v47 src0_sel:WORD_1
; DI void peer_v_phase(const Params& p) {
;     ...
;     for (int i = 0; i < 16; ++i) {
;       const float wi = (i & 3) == 0 ? r.w[i >> 2].x : (i & 3) == 1 ? r.w[i >> 2].y : (i & 3) == 2 ? r.w[i >> 2].z : r.w[i >> 2].w;
;       const f32x2 w2 = {wi, wi};
; #pragma unroll
;       for (int j = 0; j < 4; ++j) {
;         const f32x2 lo = __builtin_amdgcn_cvt_pk_f32_fp8((int)r.v[i][j], false);
;         const f32x2 hi = __builtin_amdgcn_cvt_pk_f32_fp8((int)r.v[i][j], true);
;         o2[2 * j] = __builtin_elementwise_fma(lo, w2, o2[2 * j]);
;         o2[2 * j + 1] = __builtin_elementwise_fma(hi, w2, o2[2 * j + 1]);
;       }
;     }
	v_pk_fma_f32 v[48:49], v[48:49], v[30:31], v[56:57] op_sel:[0,1,0]
	v_pk_fma_f32 v[56:57], v[58:59], v[30:31], v[64:65] op_sel:[0,1,0]
	v_pk_fma_f32 v[58:59], v[76:77], v[30:31], v[66:67] op_sel:[0,1,0]
	v_pk_fma_f32 v[28:29], v[46:47], v[30:31], v[28:29] op_sel:[0,1,0]
	v_cvt_pk_f32_fp8_e32 v[30:31], v40
	v_cvt_pk_f32_fp8_sdwa v[46:47], v40 src0_sel:WORD_1
	v_cvt_pk_f32_fp8_e32 v[64:65], v41
	v_cvt_pk_f32_fp8_sdwa v[40:41], v41 src0_sel:WORD_1
	v_pk_fma_f32 v[30:31], v[30:31], v[12:13], v[50:51] op_sel_hi:[1,0,1]
	v_pk_fma_f32 v[46:47], v[46:47], v[12:13], v[52:53] op_sel_hi:[1,0,1]
	v_pk_fma_f32 v[50:51], v[64:65], v[12:13], v[54:55] op_sel_hi:[1,0,1]
	v_pk_fma_f32 v[40:41], v[40:41], v[12:13], v[44:45] op_sel_hi:[1,0,1]
	v_cvt_pk_f32_fp8_e32 v[44:45], v42
	v_cvt_pk_f32_fp8_sdwa v[52:53], v42 src0_sel:WORD_1
	v_cvt_pk_f32_fp8_e32 v[54:55], v43
	v_cvt_pk_f32_fp8_sdwa v[42:43], v43 src0_sel:WORD_1
	v_pk_fma_f32 v[44:45], v[44:45], v[12:13], v[48:49] op_sel_hi:[1,0,1]
	v_pk_fma_f32 v[48:49], v[52:53], v[12:13], v[56:57] op_sel_hi:[1,0,1]
	v_pk_fma_f32 v[52:53], v[54:55], v[12:13], v[58:59] op_sel_hi:[1,0,1]
	v_pk_fma_f32 v[28:29], v[42:43], v[12:13], v[28:29] op_sel_hi:[1,0,1]
	v_cvt_pk_f32_fp8_e32 v[42:43], v36
	v_cvt_pk_f32_fp8_sdwa v[54:55], v36 src0_sel:WORD_1
	v_cvt_pk_f32_fp8_e32 v[56:57], v37
	v_cvt_pk_f32_fp8_sdwa v[36:37], v37 src0_sel:WORD_1
	v_pk_fma_f32 v[30:31], v[42:43], v[12:13], v[30:31] op_sel:[0,1,0]
	v_pk_fma_f32 v[42:43], v[54:55], v[12:13], v[46:47] op_sel:[0,1,0]
	v_pk_fma_f32 v[46:47], v[56:57], v[12:13], v[50:51] op_sel:[0,1,0]
	v_pk_fma_f32 v[36:37], v[36:37], v[12:13], v[40:41] op_sel:[0,1,0]
	v_cvt_pk_f32_fp8_e32 v[40:41], v38
	v_cvt_pk_f32_fp8_sdwa v[50:51], v38 src0_sel:WORD_1
	v_cvt_pk_f32_fp8_e32 v[54:55], v39
	v_cvt_pk_f32_fp8_sdwa v[38:39], v39 src0_sel:WORD_1
	v_pk_fma_f32 v[40:41], v[40:41], v[12:13], v[44:45] op_sel:[0,1,0]
	v_pk_fma_f32 v[44:45], v[50:51], v[12:13], v[48:49] op_sel:[0,1,0]
	v_pk_fma_f32 v[48:49], v[54:55], v[12:13], v[52:53] op_sel:[0,1,0]
	v_pk_fma_f32 v[12:13], v[38:39], v[12:13], v[28:29] op_sel:[0,1,0]
	v_cvt_pk_f32_fp8_e32 v[28:29], v32
	v_cvt_pk_f32_fp8_sdwa v[38:39], v32 src0_sel:WORD_1
	v_cvt_pk_f32_fp8_e32 v[50:51], v33
	v_cvt_pk_f32_fp8_sdwa v[32:33], v33 src0_sel:WORD_1
	v_pk_fma_f32 v[28:29], v[28:29], v[14:15], v[30:31] op_sel_hi:[1,0,1]
	v_pk_fma_f32 v[30:31], v[38:39], v[14:15], v[42:43] op_sel_hi:[1,0,1]
	v_pk_fma_f32 v[38:39], v[50:51], v[14:15], v[46:47] op_sel_hi:[1,0,1]
	v_pk_fma_f32 v[32:33], v[32:33], v[14:15], v[36:37] op_sel_hi:[1,0,1]
	v_cvt_pk_f32_fp8_e32 v[36:37], v34
	v_cvt_pk_f32_fp8_sdwa v[42:43], v34 src0_sel:WORD_1
	v_cvt_pk_f32_fp8_e32 v[46:47], v35
	v_cvt_pk_f32_fp8_sdwa v[34:35], v35 src0_sel:WORD_1
	v_pk_fma_f32 v[36:37], v[36:37], v[14:15], v[40:41] op_sel_hi:[1,0,1]
	v_pk_fma_f32 v[40:41], v[42:43], v[14:15], v[44:45] op_sel_hi:[1,0,1]
	v_pk_fma_f32 v[42:43], v[46:47], v[14:15], v[48:49] op_sel_hi:[1,0,1]
	v_pk_fma_f32 v[12:13], v[34:35], v[14:15], v[12:13] op_sel_hi:[1,0,1]
	v_cvt_pk_f32_fp8_e32 v[34:35], v24
	v_cvt_pk_f32_fp8_sdwa v[44:45], v24 src0_sel:WORD_1
	v_cvt_pk_f32_fp8_e32 v[46:47], v25
	v_cvt_pk_f32_fp8_sdwa v[24:25], v25 src0_sel:WORD_1
	v_pk_fma_f32 v[28:29], v[34:35], v[14:15], v[28:29] op_sel:[0,1,0]
	v_pk_fma_f32 v[30:31], v[44:45], v[14:15], v[30:31] op_sel:[0,1,0]
	v_pk_fma_f32 v[34:35], v[46:47], v[14:15], v[38:39] op_sel:[0,1,0]
	v_pk_fma_f32 v[24:25], v[24:25], v[14:15], v[32:33] op_sel:[0,1,0]
	v_cvt_pk_f32_fp8_e32 v[32:33], v26
	v_cvt_pk_f32_fp8_sdwa v[38:39], v26 src0_sel:WORD_1
	v_cvt_pk_f32_fp8_e32 v[44:45], v27
	v_cvt_pk_f32_fp8_sdwa v[26:27], v27 src0_sel:WORD_1
	v_pk_fma_f32 v[32:33], v[32:33], v[14:15], v[36:37] op_sel:[0,1,0]
	v_pk_fma_f32 v[36:37], v[38:39], v[14:15], v[40:41] op_sel:[0,1,0]
	v_pk_fma_f32 v[38:39], v[44:45], v[14:15], v[42:43] op_sel:[0,1,0]
	v_pk_fma_f32 v[12:13], v[26:27], v[14:15], v[12:13] op_sel:[0,1,0]
	v_cvt_pk_f32_fp8_e32 v[14:15], v20
	v_cvt_pk_f32_fp8_sdwa v[26:27], v20 src0_sel:WORD_1
	v_cvt_pk_f32_fp8_e32 v[40:41], v21
	v_cvt_pk_f32_fp8_sdwa v[20:21], v21 src0_sel:WORD_1
	v_pk_fma_f32 v[14:15], v[14:15], v[0:1], v[28:29] op_sel_hi:[1,0,1]
	v_pk_fma_f32 v[26:27], v[26:27], v[0:1], v[30:31] op_sel_hi:[1,0,1]
	v_pk_fma_f32 v[28:29], v[40:41], v[0:1], v[34:35] op_sel_hi:[1,0,1]
	v_pk_fma_f32 v[20:21], v[20:21], v[0:1], v[24:25] op_sel_hi:[1,0,1]
	v_cvt_pk_f32_fp8_e32 v[24:25], v22
	v_cvt_pk_f32_fp8_sdwa v[30:31], v22 src0_sel:WORD_1
	v_cvt_pk_f32_fp8_e32 v[34:35], v23
	v_cvt_pk_f32_fp8_sdwa v[22:23], v23 src0_sel:WORD_1
	v_pk_fma_f32 v[24:25], v[24:25], v[0:1], v[32:33] op_sel_hi:[1,0,1]
	v_pk_fma_f32 v[30:31], v[30:31], v[0:1], v[36:37] op_sel_hi:[1,0,1]
	v_pk_fma_f32 v[32:33], v[34:35], v[0:1], v[38:39] op_sel_hi:[1,0,1]
	v_pk_fma_f32 v[12:13], v[22:23], v[0:1], v[12:13] op_sel_hi:[1,0,1]
	v_cvt_pk_f32_fp8_e32 v[22:23], v16
	v_cvt_pk_f32_fp8_sdwa v[34:35], v16 src0_sel:WORD_1
	v_cvt_pk_f32_fp8_e32 v[36:37], v17
	v_cvt_pk_f32_fp8_sdwa v[16:17], v17 src0_sel:WORD_1
	v_pk_fma_f32 v[14:15], v[22:23], v[0:1], v[14:15] op_sel:[0,1,0]
; DI void peer_v_phase(const Params& p) {
;     ...
;     for (int i = 0; i < 16; ++i) {
;       const float wi = (i & 3) == 0 ? r.w[i >> 2].x : (i & 3) == 1 ? r.w[i >> 2].y : (i & 3) == 2 ? r.w[i >> 2].z : r.w[i >> 2].w;
;       const f32x2 w2 = {wi, wi};
; #pragma unroll
;       for (int j = 0; j < 4; ++j) {
;         const f32x2 lo = __builtin_amdgcn_cvt_pk_f32_fp8((int)r.v[i][j], false);
;         const f32x2 hi = __builtin_amdgcn_cvt_pk_f32_fp8((int)r.v[i][j], true);
;         o2[2 * j] = __builtin_elementwise_fma(lo, w2, o2[2 * j]);
;         o2[2 * j + 1] = __builtin_elementwise_fma(hi, w2, o2[2 * j + 1]);
;       }
;     }
;     float o[16];
; #pragma unroll
;     for (int k = 0; k < 8; ++k) { o[2 * k] = o2[k][0]; o[2 * k + 1] = o2[k][1]; }
;     float r8[8], r4[4], r2[2];
; #pragma unroll
;     for (int k = 0; k < 8; ++k) {
;       const float keep = (lane & 32) ? o[k + 8] : o[k], send = (lane & 32) ? o[k] : o[k + 8];
;       r8[k] = keep + __shfl_xor(send, 32);
;     }
; #pragma unroll
;     for (int k = 0; k < 4; ++k) {
;       const float keep = (lane & 16) ? r8[k + 4] : r8[k], send = (lane & 16) ? r8[k] : r8[k + 4];
;       r4[k] = keep + __shfl_xor(send, 16);
;     }
; #pragma unroll
;     for (int k = 0; k < 2; ++k) {
;       const float keep = (lane & 8) ? r4[k + 2] : r4[k], send = (lane & 8) ? r4[k] : r4[k + 2];
;       r2[k] = keep + __shfl_xor(send, 8);
;     }
;     float* xr = p.out + (size_t)tok * 1024 + 128 * g + 16 * s + 2 * q;
;     float2 y = *(const float2*)xr;
;     y.x += r2[0]; y.y += r2[1];
;     *(float2*)xr = y;
;     const float ss = wave_sum(y.x * y.x + y.y * y.y);
;     if (lane == 0) SSP[tok] = ss;
	v_pk_fma_f32 v[22:23], v[34:35], v[0:1], v[26:27] op_sel:[0,1,0]
	v_pk_fma_f32 v[26:27], v[36:37], v[0:1], v[28:29] op_sel:[0,1,0]
	v_pk_fma_f32 v[16:17], v[16:17], v[0:1], v[20:21] op_sel:[0,1,0]
	v_cvt_pk_f32_fp8_e32 v[20:21], v18
	v_cvt_pk_f32_fp8_sdwa v[28:29], v18 src0_sel:WORD_1
	v_cvt_pk_f32_fp8_e32 v[34:35], v19
	v_ashrrev_i32_e32 v205, 31, v204
	v_pk_fma_f32 v[20:21], v[20:21], v[0:1], v[24:25] op_sel:[0,1,0]
	v_pk_fma_f32 v[24:25], v[28:29], v[0:1], v[30:31] op_sel:[0,1,0]
	v_pk_fma_f32 v[28:29], v[34:35], v[0:1], v[32:33] op_sel:[0,1,0]
	v_cvt_pk_f32_fp8_sdwa v[18:19], v19 src0_sel:WORD_1
	v_cvt_pk_f32_fp8_e32 v[30:31], v9
	v_pk_fma_f32 v[0:1], v[18:19], v[0:1], v[12:13] op_sel:[0,1,0]
	v_cvt_pk_f32_fp8_e32 v[12:13], v8
	v_cvt_pk_f32_fp8_sdwa v[18:19], v8 src0_sel:WORD_1
	v_cvt_pk_f32_fp8_sdwa v[8:9], v9 src0_sel:WORD_1
	v_pk_fma_f32 v[12:13], v[12:13], v[2:3], v[14:15] op_sel_hi:[1,0,1]
	v_pk_fma_f32 v[14:15], v[18:19], v[2:3], v[22:23] op_sel_hi:[1,0,1]
	v_pk_fma_f32 v[18:19], v[30:31], v[2:3], v[26:27] op_sel_hi:[1,0,1]
	v_pk_fma_f32 v[8:9], v[8:9], v[2:3], v[16:17] op_sel_hi:[1,0,1]
	v_cvt_pk_f32_fp8_e32 v[16:17], v10
	v_cvt_pk_f32_fp8_sdwa v[22:23], v10 src0_sel:WORD_1
	v_cvt_pk_f32_fp8_e32 v[26:27], v11
	v_cvt_pk_f32_fp8_sdwa v[10:11], v11 src0_sel:WORD_1
	v_pk_fma_f32 v[16:17], v[16:17], v[2:3], v[20:21] op_sel_hi:[1,0,1]
	v_pk_fma_f32 v[20:21], v[22:23], v[2:3], v[24:25] op_sel_hi:[1,0,1]
	v_pk_fma_f32 v[22:23], v[26:27], v[2:3], v[28:29] op_sel_hi:[1,0,1]
	v_pk_fma_f32 v[0:1], v[10:11], v[2:3], v[0:1] op_sel_hi:[1,0,1]
	v_cvt_pk_f32_fp8_e32 v[10:11], v4
	v_cvt_pk_f32_fp8_sdwa v[24:25], v4 src0_sel:WORD_1
	v_cvt_pk_f32_fp8_e32 v[26:27], v5
	v_cvt_pk_f32_fp8_sdwa v[4:5], v5 src0_sel:WORD_1
	v_pk_fma_f32 v[10:11], v[10:11], v[2:3], v[12:13] op_sel:[0,1,0]
	v_pk_fma_f32 v[12:13], v[24:25], v[2:3], v[14:15] op_sel:[0,1,0]
	v_pk_fma_f32 v[14:15], v[26:27], v[2:3], v[18:19] op_sel:[0,1,0]
	v_pk_fma_f32 v[4:5], v[4:5], v[2:3], v[8:9] op_sel:[0,1,0]
	v_cvt_pk_f32_fp8_e32 v[8:9], v6
	v_cvt_pk_f32_fp8_sdwa v[18:19], v6 src0_sel:WORD_1
	v_cvt_pk_f32_fp8_e32 v[24:25], v7
	v_cvt_pk_f32_fp8_sdwa v[6:7], v7 src0_sel:WORD_1
	v_pk_fma_f32 v[8:9], v[8:9], v[2:3], v[16:17] op_sel:[0,1,0]
	v_pk_fma_f32 v[16:17], v[18:19], v[2:3], v[20:21] op_sel:[0,1,0]
	v_pk_fma_f32 v[18:19], v[24:25], v[2:3], v[22:23] op_sel:[0,1,0]
	v_pk_fma_f32 v[0:1], v[6:7], v[2:3], v[0:1] op_sel:[0,1,0]
	v_cndmask_b32_e32 v2, v10, v8, vcc
	v_cndmask_b32_e32 v3, v11, v9, vcc
	ds_bpermute_b32 v2, v210, v2
	ds_bpermute_b32 v3, v210, v3
	v_cndmask_b32_e32 v6, v12, v16, vcc
	v_cndmask_b32_e32 v7, v13, v17, vcc
	ds_bpermute_b32 v6, v210, v6
	ds_bpermute_b32 v7, v210, v7
	v_cndmask_b32_e32 v20, v14, v18, vcc
	v_cndmask_b32_e32 v21, v15, v19, vcc
	ds_bpermute_b32 v20, v210, v20
	ds_bpermute_b32 v21, v210, v21
	v_cndmask_b32_e32 v22, v4, v0, vcc
	v_cndmask_b32_e32 v23, v5, v1, vcc
	ds_bpermute_b32 v22, v210, v22
	ds_bpermute_b32 v23, v210, v23
	v_cndmask_b32_e32 v9, v9, v11, vcc
	v_cndmask_b32_e32 v8, v8, v10, vcc
	s_waitcnt lgkmcnt(6)
	v_pk_add_f32 v[2:3], v[8:9], v[2:3]
	v_cndmask_b32_e32 v9, v17, v13, vcc
	v_cndmask_b32_e32 v8, v16, v12, vcc
	s_waitcnt lgkmcnt(4)
	v_pk_add_f32 v[6:7], v[8:9], v[6:7]
	v_cndmask_b32_e32 v9, v19, v15, vcc
	v_cndmask_b32_e32 v8, v18, v14, vcc
	s_waitcnt lgkmcnt(2)
	v_pk_add_f32 v[8:9], v[8:9], v[20:21]
	v_cndmask_b32_e32 v1, v1, v5, vcc
	v_cndmask_b32_e32 v0, v0, v4, vcc
	s_waitcnt lgkmcnt(0)
	v_pk_add_f32 v[0:1], v[0:1], v[22:23]
	v_cndmask_b32_e64 v11, v9, v3, s[2:3]
	v_cndmask_b32_e64 v3, v3, v9, s[2:3]
	ds_bpermute_b32 v5, v211, v3
	v_cndmask_b32_e64 v3, v6, v0, s[2:3]
	v_cndmask_b32_e64 v4, v2, v8, s[2:3]
	ds_bpermute_b32 v12, v211, v3
	v_cndmask_b32_e64 v3, v7, v1, s[2:3]
	ds_bpermute_b32 v4, v211, v4
	ds_bpermute_b32 v13, v211, v3
	v_cndmask_b32_e64 v10, v8, v2, s[2:3]
	v_cndmask_b32_e64 v1, v1, v7, s[2:3]
	v_cndmask_b32_e64 v0, v0, v6, s[2:3]
	s_waitcnt lgkmcnt(1)
	v_pk_add_f32 v[2:3], v[10:11], v[4:5]
	s_waitcnt lgkmcnt(0)
	v_pk_add_f32 v[0:1], v[0:1], v[12:13]
	s_nop 0
	v_cndmask_b32_e64 v4, v2, v0, s[4:5]
	v_cndmask_b32_e64 v5, v3, v1, s[4:5]
	ds_bpermute_b32 v4, v212, v4
	ds_bpermute_b32 v5, v212, v5
	v_cndmask_b32_e64 v1, v1, v3, s[4:5]
	v_cndmask_b32_e64 v0, v0, v2, s[4:5]
	s_waitcnt lgkmcnt(0)
	v_pk_add_f32 v[0:1], v[0:1], v[4:5]
	s_waitcnt vmcnt(0)
	v_pk_add_f32 v[2:3], v[0:1], v[232:233]
	global_store_dwordx2 v[234:235], v[2:3], off
	v_pk_mul_f32 v[0:1], v[2:3], v[2:3]
	s_nop 0
	v_add_f32_e32 v0, v0, v1
	s_nop 1
	v_add_f32_dpp v0, v0, v0 quad_perm:[1,0,3,2] row_mask:0xf bank_mask:0xf
	s_nop 1
	v_add_f32_dpp v0, v0, v0 quad_perm:[2,3,0,1] row_mask:0xf bank_mask:0xf
	s_nop 1
	v_add_f32_dpp v0, v0, v0 row_half_mirror row_mask:0xf bank_mask:0xf
	s_nop 1
	v_add_f32_dpp v0, v0, v0 row_mirror row_mask:0xf bank_mask:0xf
	s_nop 1
	v_add_f32_dpp v0, v0, v0 row_bcast:15 row_mask:0xa bank_mask:0xf
	s_nop 1
	v_add_f32_dpp v0, v0, v0 row_bcast:31 row_mask:0xc bank_mask:0xf
	s_and_saveexec_b64 s[8:9], s[6:7]
	s_cbranch_execz .LBB0_1479
	v_mov_b32_e32 v2, v0
	v_lshl_add_u64 v[0:1], v[204:205], 2, s[12:13]
	global_store_dword v[0:1], v2, off
